# XCD-local P2->P3->P4: P2 units of an XCC's tokens run on that XCC (virtual blockIdx/gridDim + bound in m0), barriers 3 and 4 XCC-local when placement is round-robin
# baseline (speedup 1.0000x reference)
; __device__ __forceinline__ unsigned xb_ld(unsigned* p)              { return __hip_atomic_load(p, __ATOMIC_RELAXED, __HIP_MEMORY_SCOPE_AGENT); }
; __device__ __forceinline__ unsigned xb_add(unsigned* p, unsigned v) { return __hip_atomic_fetch_add(p, v, __ATOMIC_RELAXED, __HIP_MEMORY_SCOPE_AGENT); }
; #define XB_SPIN(cond, bar) do { unsigned _sp = 0; while (cond) { __builtin_amdgcn_s_sleep(1); \
;     if ((++_sp & 255u) == 0u) { if (xb_ld(&(bar)[XB_TMO])) break; if (_sp > XB_SPIN_CAP) { atomicAdd(&(bar)[XB_TMO], 1u); break; } } } } while (0)
; __device__ __forceinline__ void xcd_barrier(const XcdBarrier& b) {
;     ...
;             __builtin_amdgcn_fence(__ATOMIC_ACQUIRE, "agent");
;             xb_add(&bar[XB_XGEN(b.x)], 1u);
;             asm volatile("s_waitcnt vmcnt(0)" ::: "memory");
;         } else {
;             XB_SPIN(xb_ld(&bar[XB_XGEN(b.x)]) == gen, bar);
;             __builtin_amdgcn_fence(__ATOMIC_ACQUIRE, "agent");
;             asm volatile("s_waitcnt vmcnt(0)" ::: "memory");
;         }
.Lgb1_acq:
	buffer_inv sc1
	s_waitcnt vmcnt(0)
	ds_write_b32 v1, v5 offset:12
	v_mov_b32_e32 v2, s2
	ds_write_b32 v1, v2 offset:8
	s_waitcnt lgkmcnt(0)

; #define ATT_LOAD(KS, VS, c, set) do { const bf16_t* s_ = ((c) < 4) ? (KS) + (size_t)(64 * (c)) * 256 : (VS) + (size_t)(64 * ((c) - 4)) * 256; \
;         _Pragma("unroll") for (int it = 0; it < 4; ++it) stg[set][it] = *(const u32x4*)(s_ + (size_t)(16 * it) * 256); } while (0)
; __device__ __forceinline__ void attn_phase(LAS unsigned char* lds, const bf16_t* PROJ, const bf16_t* KM, const bf16_t* VT, bf16_t* Y, float* SS, int bx, int G, int tid) {
;     const int lane = tid & 63, wid = __builtin_amdgcn_readfirstlane(tid >> 6), fr = lane & 15, fq = lane >> 4;
;     int u = bx; if (u >= 512) return;
;     const int srow = tid >> 5, sc16 = tid & 31, sdst = srow * ATT_ROWB + ((sc16 ^ srow) << 4);
;     const int vs_ = sc16 & 3, vblk4_ = (sc16 >> 2) * 4;
;     const int rho0_ = 16 * ((srow >> 2) & 1) + 4 * (srow >> 3) + (srow & 3), vsw_ = rho0_ & 15;
;     const int vdst0 = rho0_ * ATT_ROWB + (((vblk4_ + ((2 * vs_) & 3)) ^ vsw_) << 4) + 8 * (vs_ >> 1);
;     const int frd = fr * ATT_ROWB + ((fq ^ fr) << 4);
;     int T0 = (u >> 2) * 128, h = u & 3, b = T0 / SEQ;
;     const bf16_t* ksrc = KM + ((size_t)(b * 4 + h) * 256 + srow) * 256 + sc16 * 8;
;     const bf16_t* vsrc = VT + ((size_t)(h * 4 + b) * 256 + srow) * 256 + sc16 * 8;
;     bf16x8 qf[8];
;     { const bf16_t* qp = PJ(PROJ, T0 + wid * 16 + fr, COL_Q + h * 256 + fq * 8);
; #pragma unroll
;       for (int ks = 0; ks < 8; ++ks) qf[ks] = *(const bf16x8*)(qp + ks * 512); }
;     u32x4 stg[2][4];
;     ...
;     ATT_LOAD(ksrc, vsrc, 0, 0); ATT_LOAD(ksrc, vsrc, 1, 1); ATT_WRITE(0, 0, false); __syncthreads();
; __global__ void __launch_bounds__(NTHR, 2) mk_fwd(Args a) {
;     ...
;     if (IN(3)) {
;       for (int rep = 0; rep < NREP(3); ++rep) {
;         const bool late_attn = ((bx >> 3) & 1) != 0;
;         if (!late_attn) attn_phase(lds, Proj, Kmat, VTm, Yb, SS, bx, G, tid);
;         pool_phase(lds, Proj, PoolWT, pool_scale, Yb, SS, bx, G);
;         sgu_phase(lds, Proj, VST, SguW, sgu_ln_g, sgu_ln_b, sgu_b, Yb, SS, bx, G);
;         if (late_attn) { int tid2 = threadIdx.x, bx2 = blockIdx.x; asm volatile("" : "+v"(tid2), "+s"(bx2));
;             attn_phase(lds, Proj, Kmat, VTm, Yb, SS, bx2, G, tid2); }
.LBB0_444:
	s_add_u32 s44, s24, 0x16000000
	s_addc_u32 s45, s25, 0
	s_add_u32 s46, s24, 0x3900000
	s_addc_u32 s47, s25, 0
	s_cmp_gt_i32 s26, 3
	s_cselect_b64 s[0:1], -1, 0
	s_cmp_lt_i32 s27, 4
	s_cselect_b64 s[4:5], -1, 0
	s_or_b64 s[0:1], s[0:1], s[4:5]
	s_and_b64 vcc, exec, s[0:1]
	s_cbranch_vccnz .LBB0_729
	v_mov_b32_e32 v1, s85
	ds_read_b32 v2, v1 offset:8
	ds_read_b32 v1, v1 offset:12
	s_waitcnt lgkmcnt(0)
	v_readfirstlane_b32 s0, v2
	v_readfirstlane_b32 s1, v1
	s_nop 3
	s_movk_i32 m0, 0x200
	s_cmp_eq_u32 s1, 0
	s_cbranch_scc0 .Lp2v_a
	s_and_b32 s4, s0, 7
	s_lshl_b32 s4, s4, 6
	s_lshr_b32 s5, s0, 3
	s_add_i32 s2, s4, s5
	s_movk_i32 s3, 32
	s_add_i32 m0, s4, 64
.Lp2v_a:
	s_bitcmp1_b32 s2, 3
	s_cselect_b64 s[56:57], -1, 0
	s_and_b32 s74, s2, 3
	s_lshl_b32 s0, s74, 23
	s_add_u32 s6, s36, s0
	s_addc_u32 s7, s37, 0
	s_and_b64 vcc, exec, s[56:57]
	s_cbranch_vccnz .LBB0_459
.Lattn_entry:
	s_cmp_ge_i32 s2, m0
	v_readfirstlane_b32 s0, v0
	s_cbranch_scc1 .Lattn_exit
	s_lshl_b32 s1, s2, 5
	s_and_b32 s95, s1, 0xffffff80
	s_bfe_i32 s1, s2, 0x1001a
	s_lshr_b32 s1, s1, 20
	s_add_i32 s1, s95, s1
	s_ashr_i32 s1, s1, 12
	s_lshl_b32 s4, s1, 2
	s_or_b32 s4, s4, s74
	s_ashr_i32 s5, s4, 31
	s_lshl_b64 s[4:5], s[4:5], 17
	s_lshl_b32 s10, s74, 2
	v_lshrrev_b32_e32 v3, 5, v0
	s_add_u32 s4, s40, s4
	v_and_b32_e32 v1, 15, v0
	v_lshrrev_b32_e32 v2, 4, v0
	v_lshrrev_b32_e32 v6, 3, v0
	v_lshrrev_b32_e32 v7, 6, v0
	v_lshlrev_b32_e32 v178, 9, v3
	v_mov_b32_e32 v179, 0
	s_addc_u32 s5, s41, s5
	v_bfe_u32 v67, v0, 4, 2
	s_waitcnt lgkmcnt(0)
	v_and_b32_e32 v4, 31, v0
	v_bitop3_b32 v5, v0, v3, 31 bitop3:0x6c
	v_and_b32_e32 v6, 16, v6
	v_and_b32_e32 v7, 4, v7
	v_bfe_u32 v8, v0, 5, 2
	v_bitop3_b32 v2, v2, v1, 3 bitop3:0x6c
	v_lshl_add_u64 v[190:191], s[4:5], 0, v[178:179]
	s_ashr_i32 s5, s0, 2
	v_lshlrev_b32_e32 v70, 4, v5
	v_and_b32_e32 v5, 28, v0
	v_or3_b32 v72, v7, v8, v6
	v_lshlrev_b32_e32 v6, 1, v0
	v_lshlrev_b32_e32 v74, 4, v2
	v_lshlrev_b32_e32 v75, 3, v67
	v_lshlrev_b32_e32 v2, 5, v0
	s_movk_i32 s11, 0x1e0
	v_lshlrev_b32_e32 v68, 4, v4
	v_mov_b32_e32 v69, v179
	s_add_i32 s0, s5, s95
	v_and_or_b32 v5, v6, 2, v5
	v_and_or_b32 v66, v2, s11, v75
	v_lshl_add_u64 v[30:31], v[190:191], 0, v[68:69]
	s_ashr_i32 s0, s0, 4
	s_movk_i32 s21, 0x2000
	v_bitop3_b32 v71, v7, v5, v8 bitop3:0x36
	v_lshlrev_b32_e32 v2, 1, v66
	v_mov_b32_e32 v3, v179
	s_add_i32 s4, s1, s10
	s_ashr_i32 s1, s0, 31
	v_add_co_u32_e32 v8, vcc, s21, v30
	v_lshl_add_u64 v[2:3], s[6:7], 0, v[2:3]
	s_movk_i32 s20, 0x4000
	s_lshl_b64 s[0:1], s[0:1], 13
	v_addc_co_u32_e32 v9, vcc, 0, v31, vcc
	v_lshl_add_u64 v[6:7], v[2:3], 0, s[0:1]
	s_mov_b64 s[10:11], 0xa000000
	v_add_co_u32_e32 v12, vcc, s20, v30
	v_lshlrev_b32_e32 v5, 2, v0
	v_lshl_add_u64 v[10:11], v[6:7], 0, s[10:11]
	v_addc_co_u32_e32 v13, vcc, 0, v31, vcc
	s_movk_i32 s58, 0x6000
	v_and_b32_e32 v73, 8, v5
	v_lshlrev_b32_e32 v254, 3, v4
	global_load_dwordx4 v[2:5], v[10:11], off offset:1024
	global_load_dwordx4 v[42:45], v[30:31], off
	global_load_dwordx4 v[54:57], v[8:9], off
	global_load_dwordx4 v[58:61], v[12:13], off
	v_add_co_u32_e32 v8, vcc, s58, v30
	s_mov_b32 s0, 0xa001000
	s_nop 0
	v_addc_co_u32_e32 v9, vcc, 0, v31, vcc
	v_add_co_u32_e32 v32, vcc, s0, v6
	s_mov_b32 s59, 0x8000
	s_nop 0
	v_addc_co_u32_e32 v33, vcc, 0, v7, vcc
	v_add_co_u32_e32 v34, vcc, s59, v30
	global_load_dwordx4 v[62:65], v[8:9], off
	s_nop 0
	v_addc_co_u32_e32 v35, vcc, 0, v31, vcc
	s_mov_b32 s60, 0xa000
	v_add_co_u32_e32 v38, vcc, s60, v30
	s_mov_b32 s61, 0xc000
	s_nop 0
	v_addc_co_u32_e32 v39, vcc, 0, v31, vcc
	global_load_dwordx4 v[6:9], v[10:11], off offset:2048
	s_nop 0
	global_load_dwordx4 v[10:13], v[10:11], off offset:3072
	s_nop 0
	global_load_dwordx4 v[14:17], v[32:33], off
	global_load_dwordx4 v[18:21], v[32:33], off offset:1024
	global_load_dwordx4 v[22:25], v[32:33], off offset:2048
	global_load_dwordx4 v[26:29], v[32:33], off offset:3072
	v_add_co_u32_e32 v46, vcc, s61, v30
	s_mov_b32 s70, 0xe000
	s_nop 0
	v_addc_co_u32_e32 v47, vcc, 0, v31, vcc
	v_add_co_u32_e32 v50, vcc, s70, v30
	global_load_dwordx4 v[34:37], v[34:35], off
	s_nop 0
	v_addc_co_u32_e32 v51, vcc, 0, v31, vcc
	global_load_dwordx4 v[38:41], v[38:39], off
	s_nop 0
	global_load_dwordx4 v[46:49], v[46:47], off
	s_nop 0
	global_load_dwordx4 v[30:33], v[32:33], off offset:-4096
	s_nop 0
	global_load_dwordx4 v[50:53], v[50:51], off
	v_add3_u32 v195, 0, v70, v178
	s_waitcnt vmcnt(0)
	ds_write_b128 v195, v[42:45]
	ds_write_b128 v195, v[54:57] offset:8192
	ds_write_b128 v195, v[58:61] offset:16384
	ds_write_b128 v195, v[62:65] offset:24576
	v_mbcnt_lo_u32_b32 v42, -1, 0
	v_mbcnt_hi_u32_b32 v42, -1, v42
	v_and_b32_e32 v44, 64, v42
	v_xor_b32_e32 v43, 16, v42
	v_add_u32_e32 v44, 64, v44
	v_cmp_lt_i32_e32 vcc, v43, v44
	v_lshlrev_b32_e32 v76, 9, v1
	v_lshlrev_b32_e32 v77, 4, v71
	v_lshl_add_u64 v[70:71], s[42:43], 0, v[178:179]
	s_movk_i32 s14, 0xc0
	v_cndmask_b32_e32 v43, v42, v43, vcc
	v_lshl_add_u64 v[204:205], v[70:71], 0, v[68:69]
	v_lshl_or_b32 v69, v72, 9, v73
	s_movk_i32 s12, 0x80
	v_bitop3_b32 v200, v74, s14, v76 bitop3:0x36
	s_movk_i32 s14, 0x140
	v_lshlrev_b32_e32 v215, 2, v43
	v_xor_b32_e32 v43, 32, v42
	v_bitop3_b32 v201, v74, s14, v76 bitop3:0x36
	s_movk_i32 s14, 0x180
	v_bitop3_b32 v208, v69, s12, v77 bitop3:0x36
	s_and_b32 s80, s5, -16
	v_cmp_lt_i32_e32 vcc, v43, v44
	s_lshl_b32 s5, s5, 7
	v_lshl_or_b32 v68, v1, 5, v75
	v_or_b32_e32 v196, v69, v77
	v_bitop3_b32 v199, v74, s12, v76 bitop3:0x36
	v_bitop3_b32 v202, v74, s14, v76 bitop3:0x36
	s_movk_i32 s14, 0x1c0
	v_add_u32_e32 v209, 0x1000, v208
	s_movk_i32 s12, 0x4010
	v_add_u32_e32 v213, 0x5000, v208
	v_cndmask_b32_e32 v42, v42, v43, vcc
	s_and_b32 s81, s5, 0x3800
	s_add_i32 s5, s2, s3
	v_or_b32_e32 v194, v74, v76
	s_mov_b32 s13, 0
	v_lshl_add_u64 v[184:185], s[40:41], 0, v[178:179]
	v_lshlrev_b32_e32 v197, 4, v67
	v_cmp_eq_u32_e64 s[0:1], 0, v67
	v_bitop3_b32 v198, v74, 64, v76 bitop3:0x36
	v_bitop3_b32 v203, v74, s14, v76 bitop3:0x36
	s_mov_b32 s71, 0x10000
	s_mov_b32 s72, 0x12000
	s_mov_b32 s73, 0x14000
	s_mov_b32 s75, 0x16000
	s_mov_b32 s76, 0x18000
	s_mov_b32 s77, 0x1a000
	v_add_u32_e32 v189, 0x1a000, v195
	s_mov_b32 s78, 0x1c000
	s_mov_b32 s79, 0x1e000
	v_add_u32_e32 v206, 0x1e000, v195
	v_bitop3_b32 v207, v69, 16, v77 bitop3:0x36
	v_xor_b32_e32 v210, 16, v209
	v_or_b32_e32 v211, 0x4000, v196
	v_bitop3_b32 v212, v69, s12, v77 bitop3:0x36
	v_xor_b32_e32 v214, 16, v213
	v_lshlrev_b32_e32 v216, 2, v42
	s_lshl_b32 s82, s5, 5
	s_lshl_b32 s83, s3, 5
	v_lshlrev_b32_e32 v186, 1, v68
	s_mov_b64 s[14:15], 0xc000000
	s_add_i32 s86, 0, 0x10000
	s_add_i32 s87, 0, 0x18000
	s_mov_b32 s88, 0xff61b1e6
	s_brev_b32 s89, 48
	v_lshlrev_b32_e32 v188, 1, v66
	s_movk_i32 s90, 0x3c0
	s_mov_b32 s12, s74
	s_mov_b32 s91, s2
	s_waitcnt lgkmcnt(0)
	s_barrier
	s_branch .LBB0_449

; #define LAS __attribute__((address_space(3)))
; __device__ __forceinline__ void attn_phase(LAS unsigned char* lds, const bf16_t* PROJ, const bf16_t* KM, const bf16_t* VT, bf16_t* Y, float* SS, int bx, int G, int tid) {
;     ...
;     for (;;) {
;         const int un = u + G; const bool has_next = un < 512;
;         const int T0n = has_next ? (un >> 2) * 128 : T0, hn = has_next ? (un & 3) : h, bn = T0n / SEQ;
;         const bf16_t* nksrc = KM + ((size_t)(bn * 4 + hn) * 256 + srow) * 256 + sc16 * 8;
;         const bf16_t* nvsrc = VT + ((size_t)(hn * 4 + bn) * 256 + srow) * 256 + sc16 * 8;
;         const int tok = T0 + wid * 16 + fr;
;         f32x4 st[16], ot[16];
; #pragma unroll
;         for (int i = 0; i < 16; ++i) st[i] = (f32x4){0.f, 0.f, 0.f, 0.f};
;         bf16x8 pf[8]; float linv = 0.f; u32x4 gt[8];
; #pragma unroll
;         for (int c = 0; c < 8; ++c) {
;             if (c + 2 < 8) ATT_LOAD(ksrc, vsrc, c + 2, c & 1);
;             else if (has_next) ATT_LOAD(nksrc, nvsrc, c - 6, c & 1);
;             if (c == 4) {
;                 const bf16_t* gp = PJ(PROJ, tok, COL_GC + h * 256 + 8 * fq);
; #pragma unroll
;                 for (int i = 0; i < 16; ++i) ot[i] = (f32x4){0.f, 0.f, 0.f, 0.f};
; #pragma unroll
;                 for (int p = 0; p < 8; ++p) gt[p] = *(const u32x4*)(gp + 512 * p);
;                 if (has_next) { const bf16_t* qp = PJ(PROJ, T0n + wid * 16 + fr, COL_Q + hn * 256 + fq * 8);
; #pragma unroll
;                     for (int ks = 0; ks < 8; ++ks) qf[ks] = *(const bf16x8*)(qp + ks * 512); }
;             }
;             const LAS unsigned char* base = lds + (c & 3) * ATT_BUF;
;             if (c < 4) {
;                 bf16x8 kfb[3][4];
; #pragma unroll
;                 for (int p = 0; p < 2; ++p)
; #pragma unroll
;                     for (int i = 0; i < 4; ++i) kfb[p][i] = *(const LAS bf16x8*)(base + (frd ^ (p << 6)) + i * 16 * ATT_ROWB);
; #pragma unroll
;                 for (int ks = 0; ks < 8; ++ks) {
;                     if (ks + 2 < 8) {
; #pragma unroll
;                         for (int i = 0; i < 4; ++i) kfb[(ks + 2) % 3][i] = *(const LAS bf16x8*)(base + (frd ^ ((ks + 2) << 6)) + i * 16 * ATT_ROWB); }
; #pragma unroll
;                     for (int i = 0; i < 4; ++i) st[4 * c + i] = MFMA16(kfb[ks % 3][i], qf[ks], st[4 * c + i]);
;                 }
.LBB0_449:
	v_lshlrev_b32_e32 v178, 1, v254
	v_lshl_add_u64 v[78:79], v[190:191], 0, v[178:179]
	v_add_co_u32_e32 v42, vcc, s71, v78
	v_add_u32_e32 v151, 0, v194
	s_waitcnt lgkmcnt(0)
	v_addc_co_u32_e32 v43, vcc, 0, v79, vcc
	global_load_dwordx4 v[70:73], v[42:43], off
	v_add_co_u32_e32 v42, vcc, s72, v78
	v_add_u32_e32 v150, 0, v198
	s_nop 0
	v_addc_co_u32_e32 v43, vcc, 0, v79, vcc
	global_load_dwordx4 v[74:77], v[42:43], off
	v_add_co_u32_e32 v42, vcc, s73, v78
	v_add_u32_e32 v149, 0, v199
	s_nop 0
	v_addc_co_u32_e32 v43, vcc, 0, v79, vcc
	global_load_dwordx4 v[82:85], v[42:43], off
	v_add_co_u32_e32 v42, vcc, s75, v78
	v_add_u32_e32 v148, 0, v200
	s_nop 0
	v_addc_co_u32_e32 v43, vcc, 0, v79, vcc
	global_load_dwordx4 v[66:69], v[42:43], off
	ds_read_b128 v[42:45], v151
	ds_read_b128 v[54:57], v151 offset:8192
	ds_read_b128 v[58:61], v151 offset:16384
	ds_read_b128 v[62:65], v151 offset:24576
	ds_read_b128 v[86:89], v150
	ds_read_b128 v[90:93], v150 offset:8192
	ds_read_b128 v[94:97], v150 offset:16384
	ds_read_b128 v[98:101], v150 offset:24576
	s_waitcnt lgkmcnt(7)
	v_mfma_f32_16x16x32_bf16 v[42:45], v[42:45], v[30:33], 0
	ds_read_b128 v[102:105], v149
	ds_read_b128 v[106:109], v149 offset:8192
	ds_read_b128 v[110:113], v149 offset:16384
	ds_read_b128 v[114:117], v149 offset:24576
	ds_read_b128 v[118:121], v148
	ds_read_b128 v[122:125], v148 offset:8192
	ds_read_b128 v[126:129], v148 offset:16384
	ds_read_b128 v[134:137], v148 offset:24576
	s_ashr_i32 s5, s4, 31
	s_waitcnt lgkmcnt(14)
	v_mfma_f32_16x16x32_bf16 v[54:57], v[54:57], v[30:33], 0
	s_lshl_b64 s[4:5], s[4:5], 17
	v_lshl_add_u64 v[146:147], v[204:205], 0, s[4:5]
	v_add_u32_e32 v162, s86, v194
	s_waitcnt lgkmcnt(13)
	v_mfma_f32_16x16x32_bf16 v[58:61], v[58:61], v[30:33], 0
	v_add_u32_e32 v165, s86, v198
	v_add_u32_e32 v163, s86, v199
	v_add_u32_e32 v164, s86, v200
	s_waitcnt lgkmcnt(12)
	v_mfma_f32_16x16x32_bf16 v[62:65], v[62:65], v[30:33], 0
	s_add_i32 s91, s91, s3
	s_cmp_lt_i32 s91, m0
	s_cselect_b64 s[18:19], -1, 0
	s_waitcnt lgkmcnt(11)
	v_mfma_f32_16x16x32_bf16 v[42:45], v[86:89], v[2:5], v[42:45]
	s_cmp_ge_i32 s91, m0
	s_cselect_b64 s[16:17], -1, 0
	s_and_b32 s92, s82, 0xffffff80
	s_waitcnt lgkmcnt(10)
	v_mfma_f32_16x16x32_bf16 v[54:57], v[90:93], v[2:5], v[54:57]
	s_and_b32 s93, s91, 3
	s_add_i32 s94, s95, s80
	s_lshl_b32 s4, s12, 23
	s_waitcnt lgkmcnt(9)
	v_mfma_f32_16x16x32_bf16 v[58:61], v[94:97], v[2:5], v[58:61]
	s_add_u32 s96, s36, s4
	s_addc_u32 s97, s37, 0
	s_ashr_i32 s4, s94, 4
	s_waitcnt lgkmcnt(8)
	v_mfma_f32_16x16x32_bf16 v[62:65], v[98:101], v[2:5], v[62:65]
	ds_read_b128 v[86:89], v151 offset:256
	ds_read_b128 v[90:93], v151 offset:8448
	ds_read_b128 v[94:97], v151 offset:16640
	ds_read_b128 v[98:101], v151 offset:24832
	s_ashr_i32 s5, s4, 31
	s_lshl_b64 s[4:5], s[4:5], 13
	s_waitcnt lgkmcnt(11)
	v_mfma_f32_16x16x32_bf16 v[42:45], v[102:105], v[6:9], v[42:45]
	s_add_u32 s4, s96, s4
	s_addc_u32 s5, s97, s5
	v_mov_b32_e32 v187, v179
	s_waitcnt lgkmcnt(10)
	v_mfma_f32_16x16x32_bf16 v[54:57], v[106:109], v[6:9], v[54:57]
	v_lshl_add_u64 v[130:131], s[4:5], 0, v[186:187]
	v_add_u32_e32 v187, s87, v194
	v_add_u32_e32 v220, s87, v198
	s_waitcnt lgkmcnt(9)
	v_mfma_f32_16x16x32_bf16 v[58:61], v[110:113], v[6:9], v[58:61]
	v_add_u32_e32 v221, s87, v199
	v_add_u32_e32 v222, s87, v200
	v_add_u32_e32 v219, s87, v201
	s_waitcnt lgkmcnt(8)
	v_mfma_f32_16x16x32_bf16 v[62:65], v[114:117], v[6:9], v[62:65]
	ds_read_b128 v[102:105], v150 offset:256
	ds_read_b128 v[106:109], v150 offset:8448
	ds_read_b128 v[110:113], v150 offset:16640
	ds_read_b128 v[114:117], v150 offset:24832
	v_add_u32_e32 v218, s87, v202
	v_add_u32_e32 v217, s87, v203
	s_waitcnt lgkmcnt(11)
	v_mfma_f32_16x16x32_bf16 v[42:45], v[118:121], v[10:13], v[42:45]
	v_lshl_add_u64 v[132:133], v[130:131], 0, s[14:15]
	s_waitcnt lgkmcnt(10)
	v_mfma_f32_16x16x32_bf16 v[54:57], v[122:125], v[10:13], v[54:57]
	s_waitcnt lgkmcnt(9)
	v_mfma_f32_16x16x32_bf16 v[58:61], v[126:129], v[10:13], v[58:61]
	s_waitcnt lgkmcnt(8)
	v_mfma_f32_16x16x32_bf16 v[62:65], v[134:137], v[10:13], v[62:65]
	ds_read_b128 v[118:121], v149 offset:256
	ds_read_b128 v[122:125], v149 offset:8448
	ds_read_b128 v[126:129], v149 offset:16640
	ds_read_b128 v[134:137], v149 offset:24832
	s_waitcnt lgkmcnt(11)
	v_mfma_f32_16x16x32_bf16 v[42:45], v[86:89], v[14:17], v[42:45]
	s_waitcnt lgkmcnt(10)
	v_mfma_f32_16x16x32_bf16 v[54:57], v[90:93], v[14:17], v[54:57]
	s_waitcnt lgkmcnt(9)
	v_mfma_f32_16x16x32_bf16 v[58:61], v[94:97], v[14:17], v[58:61]
	s_waitcnt lgkmcnt(8)
	v_mfma_f32_16x16x32_bf16 v[62:65], v[98:101], v[14:17], v[62:65]
	ds_read_b128 v[86:89], v148 offset:256
	ds_read_b128 v[90:93], v148 offset:8448
	ds_read_b128 v[94:97], v148 offset:16640
	ds_read_b128 v[98:101], v148 offset:24832
	s_waitcnt vmcnt(15)
	ds_write_b128 v195, v[34:37] offset:32768
	s_waitcnt vmcnt(14)
	ds_write_b128 v195, v[38:41] offset:40960
	s_waitcnt vmcnt(13)
	ds_write_b128 v195, v[46:49] offset:49152
	s_waitcnt vmcnt(12)
	ds_write_b128 v195, v[50:53] offset:57344
	v_add_co_u32_e32 v34, vcc, s76, v78
	s_waitcnt lgkmcnt(0)
	s_nop 0
	v_addc_co_u32_e32 v35, vcc, 0, v79, vcc
	s_barrier
; #define LAS __attribute__((address_space(3)))
; #define MFMA16(a, b, c) __builtin_amdgcn_mfma_f32_16x16x32_bf16((a), (b), (c), 0, 0, 0)
; __device__ __forceinline__ void attn_phase(LAS unsigned char* lds, const bf16_t* PROJ, const bf16_t* KM, const bf16_t* VT, bf16_t* Y, float* SS, int bx, int G, int tid) {
;     ...
;             if (c < 4) {
;                 bf16x8 kfb[3][4];
; #pragma unroll
;                 for (int p = 0; p < 2; ++p)
; #pragma unroll
;                     for (int i = 0; i < 4; ++i) kfb[p][i] = *(const LAS bf16x8*)(base + (frd ^ (p << 6)) + i * 16 * ATT_ROWB);
; #pragma unroll
;                 for (int ks = 0; ks < 8; ++ks) {
;                     if (ks + 2 < 8) {
; #pragma unroll
;                         for (int i = 0; i < 4; ++i) kfb[(ks + 2) % 3][i] = *(const LAS bf16x8*)(base + (frd ^ ((ks + 2) << 6)) + i * 16 * ATT_ROWB); }
; #pragma unroll
;                     for (int i = 0; i < 4; ++i) st[4 * c + i] = MFMA16(kfb[ks % 3][i], qf[ks], st[4 * c + i]);
;                 }
	global_load_dwordx4 v[38:41], v[34:35], off
	v_add_co_u32_e32 v34, vcc, s77, v78
	v_mfma_f32_16x16x32_bf16 v[42:45], v[102:105], v[18:21], v[42:45]
	s_nop 0
	v_addc_co_u32_e32 v35, vcc, 0, v79, vcc
	v_add_co_u32_e32 v46, vcc, s78, v78
	v_mfma_f32_16x16x32_bf16 v[54:57], v[106:109], v[18:21], v[54:57]
	s_nop 0
	v_addc_co_u32_e32 v47, vcc, 0, v79, vcc
	v_add_co_u32_e32 v50, vcc, s79, v78
	v_mfma_f32_16x16x32_bf16 v[58:61], v[110:113], v[18:21], v[58:61]
	global_load_dwordx4 v[34:37], v[34:35], off
	v_addc_co_u32_e32 v51, vcc, 0, v79, vcc
	v_mfma_f32_16x16x32_bf16 v[62:65], v[114:117], v[18:21], v[62:65]
	global_load_dwordx4 v[46:49], v[46:47], off
	s_nop 0
	global_load_dwordx4 v[50:53], v[50:51], off
	v_mfma_f32_16x16x32_bf16 v[42:45], v[118:121], v[22:25], v[42:45]
	v_mfma_f32_16x16x32_bf16 v[54:57], v[122:125], v[22:25], v[54:57]
	v_mfma_f32_16x16x32_bf16 v[102:105], v[126:129], v[22:25], v[58:61]
	v_mfma_f32_16x16x32_bf16 v[106:109], v[134:137], v[22:25], v[62:65]
	v_mfma_f32_16x16x32_bf16 v[62:65], v[86:89], v[26:29], v[42:45]
	v_mfma_f32_16x16x32_bf16 v[58:61], v[90:93], v[26:29], v[54:57]
	v_mfma_f32_16x16x32_bf16 v[54:57], v[94:97], v[26:29], v[102:105]
	v_mfma_f32_16x16x32_bf16 v[42:45], v[98:101], v[26:29], v[106:109]
	ds_read_b128 v[78:81], v151 offset:32768
	ds_read_b128 v[86:89], v151 offset:40960
	ds_read_b128 v[90:93], v151 offset:49152
	ds_read_b128 v[94:97], v151 offset:57344
	ds_read_b128 v[98:101], v150 offset:32768
	ds_read_b128 v[102:105], v150 offset:40960
	ds_read_b128 v[106:109], v150 offset:49152
	ds_read_b128 v[110:113], v150 offset:57344
	ds_read_b128 v[114:117], v149 offset:32768
	ds_read_b128 v[118:121], v149 offset:40960
	ds_read_b128 v[122:125], v149 offset:49152
	ds_read_b128 v[126:129], v149 offset:57344
	ds_read_b128 v[134:137], v148 offset:32768
	ds_read_b128 v[138:141], v148 offset:40960
	ds_read_b128 v[142:145], v148 offset:49152
	ds_read_b128 v[152:155], v148 offset:57344
	s_waitcnt lgkmcnt(14)
	v_mfma_f32_16x16x32_bf16 v[78:81], v[78:81], v[30:33], 0
	s_waitcnt lgkmcnt(12)
	v_mfma_f32_16x16x32_bf16 v[94:97], v[94:97], v[30:33], 0
	s_waitcnt lgkmcnt(11)
	v_mfma_f32_16x16x32_bf16 v[78:81], v[98:101], v[2:5], v[78:81]
	v_mfma_f32_16x16x32_bf16 v[86:89], v[86:89], v[30:33], 0
	s_waitcnt lgkmcnt(8)
	v_mfma_f32_16x16x32_bf16 v[94:97], v[110:113], v[2:5], v[94:97]
	s_waitcnt lgkmcnt(7)
	v_mfma_f32_16x16x32_bf16 v[78:81], v[114:117], v[6:9], v[78:81]
	v_mfma_f32_16x16x32_bf16 v[90:93], v[90:93], v[30:33], 0
	v_mfma_f32_16x16x32_bf16 v[86:89], v[102:105], v[2:5], v[86:89]
	s_waitcnt lgkmcnt(4)
	v_mfma_f32_16x16x32_bf16 v[94:97], v[126:129], v[6:9], v[94:97]
	s_waitcnt lgkmcnt(3)
	v_mfma_f32_16x16x32_bf16 v[78:81], v[134:137], v[10:13], v[78:81]
	v_mfma_f32_16x16x32_bf16 v[90:93], v[106:109], v[2:5], v[90:93]
	ds_read_b128 v[98:101], v151 offset:33024
	ds_read_b128 v[102:105], v151 offset:41216
	ds_read_b128 v[106:109], v151 offset:49408
	ds_read_b128 v[110:113], v151 offset:57600
	v_mfma_f32_16x16x32_bf16 v[86:89], v[118:121], v[6:9], v[86:89]
	s_waitcnt lgkmcnt(4)
	v_mfma_f32_16x16x32_bf16 v[94:97], v[152:155], v[10:13], v[94:97]
	s_waitcnt lgkmcnt(3)
	v_mfma_f32_16x16x32_bf16 v[78:81], v[98:101], v[14:17], v[78:81]
	v_mfma_f32_16x16x32_bf16 v[90:93], v[122:125], v[6:9], v[90:93]
	ds_read_b128 v[114:117], v150 offset:33024
	ds_read_b128 v[118:121], v150 offset:41216
	ds_read_b128 v[122:125], v150 offset:49408
	ds_read_b128 v[126:129], v150 offset:57600
	v_mfma_f32_16x16x32_bf16 v[86:89], v[138:141], v[10:13], v[86:89]
	s_waitcnt lgkmcnt(4)
	v_mfma_f32_16x16x32_bf16 v[94:97], v[110:113], v[14:17], v[94:97]
	s_waitcnt lgkmcnt(3)
	v_mfma_f32_16x16x32_bf16 v[78:81], v[114:117], v[18:21], v[78:81]
	v_mfma_f32_16x16x32_bf16 v[90:93], v[142:145], v[10:13], v[90:93]
	ds_read_b128 v[134:137], v149 offset:33024
	ds_read_b128 v[138:141], v149 offset:41216
	ds_read_b128 v[142:145], v149 offset:49408
	ds_read_b128 v[152:155], v149 offset:57600
	v_mfma_f32_16x16x32_bf16 v[86:89], v[102:105], v[14:17], v[86:89]
	s_waitcnt lgkmcnt(4)
	v_mfma_f32_16x16x32_bf16 v[94:97], v[126:129], v[18:21], v[94:97]
	s_waitcnt lgkmcnt(3)
	v_mfma_f32_16x16x32_bf16 v[78:81], v[134:137], v[22:25], v[78:81]
	v_mfma_f32_16x16x32_bf16 v[90:93], v[106:109], v[14:17], v[90:93]
	ds_read_b128 v[98:101], v148 offset:33024
	ds_read_b128 v[102:105], v148 offset:41216
	ds_read_b128 v[106:109], v148 offset:49408
	ds_read_b128 v[110:113], v148 offset:57600
	v_mfma_f32_16x16x32_bf16 v[86:89], v[118:121], v[18:21], v[86:89]
	s_waitcnt lgkmcnt(4)
	v_mfma_f32_16x16x32_bf16 v[118:121], v[152:155], v[22:25], v[94:97]
	s_waitcnt lgkmcnt(3)
	v_mfma_f32_16x16x32_bf16 v[94:97], v[98:101], v[26:29], v[78:81]
	v_add_u32_e32 v98, 0x10000, v195
	s_waitcnt vmcnt(7)
	ds_write_b128 v98, v[70:73]
	v_add_u32_e32 v70, 0x12000, v195
	v_mfma_f32_16x16x32_bf16 v[90:93], v[122:125], v[18:21], v[90:93]
	s_waitcnt vmcnt(6)
	ds_write_b128 v70, v[74:77]
	v_add_u32_e32 v70, 0x14000, v195
	s_waitcnt vmcnt(5)
	ds_write_b128 v70, v[82:85]
	v_add_u32_e32 v70, 0x16000, v195
	s_waitcnt vmcnt(4)
	ds_write_b128 v70, v[66:69]
	v_add_co_u32_e32 v66, vcc, s21, v146
	v_mfma_f32_16x16x32_bf16 v[86:89], v[138:141], v[22:25], v[86:89]
	s_nop 0
	v_addc_co_u32_e32 v67, vcc, 0, v147, vcc
	s_waitcnt lgkmcnt(0)
	v_mfma_f32_16x16x32_bf16 v[114:117], v[142:145], v[22:25], v[90:93]
	s_barrier
; #define LAS __attribute__((address_space(3)))
; #define MFMA16(a, b, c) __builtin_amdgcn_mfma_f32_16x16x32_bf16((a), (b), (c), 0, 0, 0)
; __device__ __forceinline__ void attn_phase(LAS unsigned char* lds, const bf16_t* PROJ, const bf16_t* KM, const bf16_t* VT, bf16_t* Y, float* SS, int bx, int G, int tid) {
;     ...
;             if (c < 4) {
;                 bf16x8 kfb[3][4];
; #pragma unroll
;                 for (int p = 0; p < 2; ++p)
; #pragma unroll
;                     for (int i = 0; i < 4; ++i) kfb[p][i] = *(const LAS bf16x8*)(base + (frd ^ (p << 6)) + i * 16 * ATT_ROWB);
; #pragma unroll
;                 for (int ks = 0; ks < 8; ++ks) {
;                     if (ks + 2 < 8) {
; #pragma unroll
;                         for (int i = 0; i < 4; ++i) kfb[(ks + 2) % 3][i] = *(const LAS bf16x8*)(base + (frd ^ ((ks + 2) << 6)) + i * 16 * ATT_ROWB); }
; #pragma unroll
;                     for (int i = 0; i < 4; ++i) st[4 * c + i] = MFMA16(kfb[ks % 3][i], qf[ks], st[4 * c + i]);
;                 }
	global_load_dwordx4 v[82:85], v[146:147], off
	global_load_dwordx4 v[74:77], v[66:67], off
	v_add_co_u32_e32 v66, vcc, s20, v146
	v_mfma_f32_16x16x32_bf16 v[90:93], v[102:105], v[26:29], v[86:89]
	s_nop 0
	v_addc_co_u32_e32 v67, vcc, 0, v147, vcc
	global_load_dwordx4 v[70:73], v[66:67], off
	v_add_co_u32_e32 v66, vcc, s58, v146
	v_mfma_f32_16x16x32_bf16 v[86:89], v[106:109], v[26:29], v[114:117]
	s_nop 0
	v_addc_co_u32_e32 v67, vcc, 0, v147, vcc
	global_load_dwordx4 v[66:69], v[66:67], off
	v_mfma_f32_16x16x32_bf16 v[78:81], v[110:113], v[26:29], v[118:121]
	ds_read_b128 v[98:101], v162
	ds_read_b128 v[102:105], v162 offset:8192
	ds_read_b128 v[106:109], v162 offset:16384
	ds_read_b128 v[110:113], v162 offset:24576
	ds_read_b128 v[118:121], v165
	ds_read_b128 v[122:125], v165 offset:8192
	ds_read_b128 v[126:129], v165 offset:16384
	ds_read_b128 v[134:137], v165 offset:24576
	ds_read_b128 v[138:141], v163
	ds_read_b128 v[142:145], v163 offset:8192
	ds_read_b128 v[152:155], v163 offset:16384
	ds_read_b128 v[114:117], v163 offset:24576
	s_waitcnt lgkmcnt(11)
	v_mfma_f32_16x16x32_bf16 v[156:159], v[98:101], v[30:33], 0
	s_waitcnt lgkmcnt(9)
	v_mfma_f32_16x16x32_bf16 v[170:173], v[106:109], v[30:33], 0
	s_waitcnt lgkmcnt(8)
	v_mfma_f32_16x16x32_bf16 v[174:177], v[110:113], v[30:33], 0
	s_waitcnt lgkmcnt(7)
	v_mfma_f32_16x16x32_bf16 v[156:159], v[118:121], v[2:5], v[156:159]
	s_waitcnt lgkmcnt(5)
	v_mfma_f32_16x16x32_bf16 v[126:129], v[126:129], v[2:5], v[170:173]
	s_waitcnt lgkmcnt(4)
	v_mfma_f32_16x16x32_bf16 v[134:137], v[134:137], v[2:5], v[174:177]
	v_mfma_f32_16x16x32_bf16 v[166:169], v[102:105], v[30:33], 0
	ds_read_b128 v[110:113], v164
	ds_read_b128 v[106:109], v164 offset:8192
	ds_read_b128 v[98:101], v164 offset:16384
	ds_read_b128 v[102:105], v164 offset:24576
	s_waitcnt lgkmcnt(7)
	v_mfma_f32_16x16x32_bf16 v[138:141], v[138:141], v[6:9], v[156:159]
	s_waitcnt lgkmcnt(5)
	v_mfma_f32_16x16x32_bf16 v[126:129], v[152:155], v[6:9], v[126:129]
	s_waitcnt lgkmcnt(4)
	v_mfma_f32_16x16x32_bf16 v[114:117], v[114:117], v[6:9], v[134:137]
	v_mfma_f32_16x16x32_bf16 v[122:125], v[122:125], v[2:5], v[166:169]
	ds_read_b128 v[118:121], v162 offset:256
	s_nop 1
	ds_read_b128 v[168:171], v162 offset:8448
	ds_read_b128 v[172:175], v162 offset:16640
	ds_read_b128 v[190:193], v162 offset:24832
	v_add_u32_e32 v166, s86, v201
	v_add_u32_e32 v167, s86, v202
	s_waitcnt lgkmcnt(7)
	v_mfma_f32_16x16x32_bf16 v[110:113], v[110:113], v[10:13], v[138:141]
	s_waitcnt lgkmcnt(5)
	v_mfma_f32_16x16x32_bf16 v[98:101], v[98:101], v[10:13], v[126:129]
	s_waitcnt lgkmcnt(4)
	v_mfma_f32_16x16x32_bf16 v[102:105], v[102:105], v[10:13], v[114:117]
	v_mfma_f32_16x16x32_bf16 v[122:125], v[142:145], v[6:9], v[122:125]
	ds_read_b128 v[134:137], v166
	ds_read_b128 v[142:145], v166 offset:8192
	ds_read_b128 v[152:155], v166 offset:16384
	ds_read_b128 v[156:159], v166 offset:24576
	s_waitcnt lgkmcnt(7)
	v_mfma_f32_16x16x32_bf16 v[110:113], v[118:121], v[14:17], v[110:113]
	s_waitcnt lgkmcnt(5)
	v_mfma_f32_16x16x32_bf16 v[98:101], v[172:175], v[14:17], v[98:101]
	s_waitcnt lgkmcnt(4)
	v_mfma_f32_16x16x32_bf16 v[102:105], v[190:193], v[14:17], v[102:105]
	v_mfma_f32_16x16x32_bf16 v[106:109], v[106:109], v[10:13], v[122:125]
	ds_read_b128 v[114:117], v167
	s_nop 1
	ds_read_b128 v[122:125], v167 offset:8192
	ds_read_b128 v[126:129], v167 offset:16384
	ds_read_b128 v[138:141], v167 offset:24576
	s_waitcnt lgkmcnt(7)
	v_mfma_f32_16x16x32_bf16 v[110:113], v[134:137], v[18:21], v[110:113]
	s_waitcnt lgkmcnt(5)
	v_mfma_f32_16x16x32_bf16 v[98:101], v[152:155], v[18:21], v[98:101]
	s_waitcnt lgkmcnt(4)
	v_mfma_f32_16x16x32_bf16 v[102:105], v[156:159], v[18:21], v[102:105]
	v_mfma_f32_16x16x32_bf16 v[106:109], v[168:171], v[14:17], v[106:109]
	v_add_u32_e32 v168, s86, v203
	ds_read_b128 v[118:121], v168
	ds_read_b128 v[170:173], v168 offset:8192
	ds_read_b128 v[174:177], v168 offset:16384
	ds_read_b128 v[190:193], v168 offset:24576
	s_waitcnt lgkmcnt(7)
	v_mfma_f32_16x16x32_bf16 v[110:113], v[114:117], v[22:25], v[110:113]
	s_waitcnt lgkmcnt(5)
	v_mfma_f32_16x16x32_bf16 v[98:101], v[126:129], v[22:25], v[98:101]
	s_waitcnt lgkmcnt(4)
	v_mfma_f32_16x16x32_bf16 v[114:117], v[138:141], v[22:25], v[102:105]
	s_waitcnt lgkmcnt(1)
	v_mfma_f32_16x16x32_bf16 v[102:105], v[174:177], v[26:29], v[98:101]
	s_waitcnt lgkmcnt(0)
	v_mfma_f32_16x16x32_bf16 v[98:101], v[190:193], v[26:29], v[114:117]
	s_nop 3
	v_add_u32_e32 v114, 0x18000, v195
	s_waitcnt vmcnt(7)
	ds_write_b128 v114, v[38:41]
	s_waitcnt vmcnt(6)
	ds_write_b128 v189, v[34:37]
	v_add_u32_e32 v34, 0x1c000, v195
	s_waitcnt vmcnt(5)
	ds_write_b128 v34, v[46:49]
	s_waitcnt vmcnt(4)
	ds_write_b128 v206, v[50:53]
	v_add_co_u32_e32 v34, vcc, s59, v146
	v_mfma_f32_16x16x32_bf16 v[106:109], v[142:145], v[18:21], v[106:109]
	s_nop 0
	v_addc_co_u32_e32 v35, vcc, 0, v147, vcc
	v_add_co_u32_e32 v38, vcc, s60, v146
	s_waitcnt lgkmcnt(0)
	s_nop 0
	v_addc_co_u32_e32 v39, vcc, 0, v147, vcc
	s_barrier
; #define LAS __attribute__((address_space(3)))
; #define MFMA16(a, b, c) __builtin_amdgcn_mfma_f32_16x16x32_bf16((a), (b), (c), 0, 0, 0)
; __device__ __forceinline__ void attn_phase(LAS unsigned char* lds, const bf16_t* PROJ, const bf16_t* KM, const bf16_t* VT, bf16_t* Y, float* SS, int bx, int G, int tid) {
;     ...
;             if (c < 4) {
;                 bf16x8 kfb[3][4];
; #pragma unroll
;                 for (int p = 0; p < 2; ++p)
; #pragma unroll
;                     for (int i = 0; i < 4; ++i) kfb[p][i] = *(const LAS bf16x8*)(base + (frd ^ (p << 6)) + i * 16 * ATT_ROWB);
; #pragma unroll
;                 for (int ks = 0; ks < 8; ++ks) {
;                     if (ks + 2 < 8) {
; #pragma unroll
;                         for (int i = 0; i < 4; ++i) kfb[(ks + 2) % 3][i] = *(const LAS bf16x8*)(base + (frd ^ ((ks + 2) << 6)) + i * 16 * ATT_ROWB); }
; #pragma unroll
;                     for (int i = 0; i < 4; ++i) st[4 * c + i] = MFMA16(kfb[ks % 3][i], qf[ks], st[4 * c + i]);
;                 }
;                 if (c == 3) {
;                     float mx = -3.0e38f;
; #pragma unroll
;                     for (int i = 0; i < 16; ++i) mx = fmaxf(fmaxf(mx, fmaxf(st[i][0], st[i][1])), fmaxf(st[i][2], st[i][3]));
	global_load_dwordx4 v[34:37], v[34:35], off
	v_mfma_f32_16x16x32_bf16 v[106:109], v[122:125], v[22:25], v[106:109]
	global_load_dwordx4 v[50:53], v[38:39], off
	v_add_co_u32_e32 v38, vcc, s61, v146
	v_mfma_f32_16x16x32_bf16 v[110:113], v[118:121], v[26:29], v[110:113]
	s_nop 0
	v_addc_co_u32_e32 v39, vcc, 0, v147, vcc
	global_load_dwordx4 v[46:49], v[38:39], off
	v_add_co_u32_e32 v38, vcc, s70, v146
	v_mfma_f32_16x16x32_bf16 v[106:109], v[170:173], v[26:29], v[106:109]
	s_nop 0
	v_addc_co_u32_e32 v39, vcc, 0, v147, vcc
	global_load_dwordx4 v[38:41], v[38:39], off
	ds_read_b128 v[114:117], v187
	ds_read_b128 v[118:121], v187 offset:8192
	ds_read_b128 v[122:125], v187 offset:16384
	ds_read_b128 v[126:129], v187 offset:24576
	s_waitcnt lgkmcnt(3)
	v_mfma_f32_16x16x32_bf16 v[114:117], v[114:117], v[30:33], 0
	ds_read_b128 v[134:137], v220
	ds_read_b128 v[138:141], v220 offset:8192
	ds_read_b128 v[142:145], v220 offset:16384
	ds_read_b128 v[152:155], v220 offset:24576
	ds_read_b128 v[156:159], v221
	ds_read_b128 v[170:173], v221 offset:8192
	ds_read_b128 v[174:177], v221 offset:16384
	ds_read_b128 v[190:193], v221 offset:24576
	ds_read_b128 v[224:227], v222
	ds_read_b128 v[228:231], v222 offset:8192
	ds_read_b128 v[232:235], v222 offset:16384
	ds_read_b128 v[236:239], v222 offset:24576
	s_waitcnt lgkmcnt(12)
	v_mfma_f32_16x16x32_bf16 v[126:129], v[126:129], v[30:33], 0
	s_waitcnt lgkmcnt(11)
	v_mfma_f32_16x16x32_bf16 v[114:117], v[134:137], v[2:5], v[114:117]
	v_mfma_f32_16x16x32_bf16 v[118:121], v[118:121], v[30:33], 0
	s_waitcnt lgkmcnt(8)
	v_mfma_f32_16x16x32_bf16 v[126:129], v[152:155], v[2:5], v[126:129]
	s_waitcnt lgkmcnt(7)
	v_mfma_f32_16x16x32_bf16 v[114:117], v[156:159], v[6:9], v[114:117]
	v_mfma_f32_16x16x32_bf16 v[122:125], v[122:125], v[30:33], 0
	v_mfma_f32_16x16x32_bf16 v[118:121], v[138:141], v[2:5], v[118:121]
	s_waitcnt lgkmcnt(4)
	v_mfma_f32_16x16x32_bf16 v[126:129], v[190:193], v[6:9], v[126:129]
	s_waitcnt lgkmcnt(3)
	v_mfma_f32_16x16x32_bf16 v[114:117], v[224:227], v[10:13], v[114:117]
	v_mfma_f32_16x16x32_bf16 v[122:125], v[142:145], v[2:5], v[122:125]
	ds_read_b128 v[134:137], v187 offset:256
	ds_read_b128 v[138:141], v187 offset:8448
	ds_read_b128 v[142:145], v187 offset:16640
	ds_read_b128 v[152:155], v187 offset:24832
	v_mfma_f32_16x16x32_bf16 v[118:121], v[170:173], v[6:9], v[118:121]
	s_waitcnt lgkmcnt(4)
	v_mfma_f32_16x16x32_bf16 v[126:129], v[236:239], v[10:13], v[126:129]
	s_waitcnt lgkmcnt(3)
	v_mfma_f32_16x16x32_bf16 v[114:117], v[134:137], v[14:17], v[114:117]
	v_mfma_f32_16x16x32_bf16 v[122:125], v[174:177], v[6:9], v[122:125]
	ds_read_b128 v[156:159], v219
	ds_read_b128 v[170:173], v219 offset:8192
	ds_read_b128 v[174:177], v219 offset:16384
	ds_read_b128 v[190:193], v219 offset:24576
	v_mfma_f32_16x16x32_bf16 v[118:121], v[228:231], v[10:13], v[118:121]
	s_waitcnt lgkmcnt(4)
	v_mfma_f32_16x16x32_bf16 v[126:129], v[152:155], v[14:17], v[126:129]
	s_waitcnt lgkmcnt(3)
	v_mfma_f32_16x16x32_bf16 v[114:117], v[156:159], v[18:21], v[114:117]
	v_mfma_f32_16x16x32_bf16 v[122:125], v[232:235], v[10:13], v[122:125]
	ds_read_b128 v[224:227], v218
	ds_read_b128 v[228:231], v218 offset:8192
	ds_read_b128 v[232:235], v218 offset:16384
	ds_read_b128 v[236:239], v218 offset:24576
	v_mfma_f32_16x16x32_bf16 v[118:121], v[138:141], v[14:17], v[118:121]
	s_waitcnt lgkmcnt(4)
	v_mfma_f32_16x16x32_bf16 v[126:129], v[190:193], v[18:21], v[126:129]
	s_waitcnt lgkmcnt(3)
	v_mfma_f32_16x16x32_bf16 v[114:117], v[224:227], v[22:25], v[114:117]
	v_mfma_f32_16x16x32_bf16 v[122:125], v[142:145], v[14:17], v[122:125]
	ds_read_b128 v[134:137], v217
	ds_read_b128 v[138:141], v217 offset:8192
	ds_read_b128 v[142:145], v217 offset:16384
	ds_read_b128 v[152:155], v217 offset:24576
	v_mfma_f32_16x16x32_bf16 v[118:121], v[170:173], v[18:21], v[118:121]
	s_waitcnt lgkmcnt(4)
	v_mfma_f32_16x16x32_bf16 v[170:173], v[236:239], v[22:25], v[126:129]
	s_waitcnt lgkmcnt(3)
	v_mfma_f32_16x16x32_bf16 v[126:129], v[134:137], v[26:29], v[114:117]
	v_max_f32_e32 v134, v63, v63
	v_max_f32_e32 v135, v62, v62
	v_max_f32_e32 v134, v135, v134
	v_max_f32_e32 v135, v65, v65
	v_max_f32_e32 v136, v64, v64
	v_max_f32_e32 v135, v136, v135
	v_max3_f32 v134, v134, s88, v135
	v_max_f32_e32 v135, v59, v59
	v_max_f32_e32 v136, v58, v58
	v_max_f32_e32 v135, v136, v135
	v_max_f32_e32 v136, v61, v61
	v_max_f32_e32 v137, v60, v60
	v_max_f32_e32 v136, v137, v136
	v_max3_f32 v134, v134, v135, v136
	v_max_f32_e32 v135, v55, v55
	v_max_f32_e32 v136, v54, v54
	v_max_f32_e32 v135, v136, v135
	v_max_f32_e32 v136, v57, v57
	v_max_f32_e32 v137, v56, v56
	v_max_f32_e32 v136, v137, v136
	v_max3_f32 v134, v134, v135, v136
	v_max_f32_e32 v135, v43, v43
	v_max_f32_e32 v136, v42, v42
	v_max_f32_e32 v135, v136, v135
	v_max_f32_e32 v136, v45, v45
	v_max_f32_e32 v137, v44, v44
	v_max_f32_e32 v136, v137, v136
	v_max3_f32 v134, v134, v135, v136
	v_max_f32_e32 v135, v95, v95
	v_max_f32_e32 v136, v94, v94
	v_max_f32_e32 v135, v136, v135
	v_max_f32_e32 v136, v97, v97
	v_max_f32_e32 v137, v96, v96
	v_max_f32_e32 v136, v137, v136
	v_max3_f32 v134, v134, v135, v136
	v_max_f32_e32 v135, v91, v91
	v_max_f32_e32 v136, v90, v90
	v_max_f32_e32 v135, v136, v135
	v_max_f32_e32 v136, v93, v93
	v_max_f32_e32 v137, v92, v92
	v_max_f32_e32 v136, v137, v136
	v_max3_f32 v134, v134, v135, v136
	v_max_f32_e32 v135, v87, v87
	v_max_f32_e32 v136, v86, v86
	v_max_f32_e32 v135, v136, v135
	v_max_f32_e32 v136, v89, v89
	v_max_f32_e32 v137, v88, v88
	v_max_f32_e32 v136, v137, v136
	v_max3_f32 v134, v134, v135, v136
	v_max_f32_e32 v135, v79, v79
	v_max_f32_e32 v136, v78, v78
	v_max_f32_e32 v135, v136, v135
	v_max_f32_e32 v136, v81, v81
	v_max_f32_e32 v137, v80, v80
	v_max_f32_e32 v136, v137, v136
	v_max3_f32 v134, v134, v135, v136
	v_max_f32_e32 v135, v111, v111
	v_max_f32_e32 v136, v110, v110
	v_max_f32_e32 v135, v136, v135
	v_max_f32_e32 v136, v113, v113
	v_max_f32_e32 v137, v112, v112
	v_max_f32_e32 v136, v137, v136
	v_max3_f32 v134, v134, v135, v136
	v_max_f32_e32 v135, v107, v107
	v_max_f32_e32 v136, v106, v106
	v_max_f32_e32 v135, v136, v135
	v_max_f32_e32 v136, v109, v109
	v_max_f32_e32 v137, v108, v108
	v_max_f32_e32 v136, v137, v136
	v_mfma_f32_16x16x32_bf16 v[122:125], v[174:177], v[18:21], v[122:125]
	v_max3_f32 v134, v134, v135, v136
	v_max_f32_e32 v135, v103, v103
	v_max_f32_e32 v136, v102, v102
	v_mfma_f32_16x16x32_bf16 v[118:121], v[228:231], v[22:25], v[118:121]
	v_max_f32_e32 v135, v136, v135
	v_max_f32_e32 v136, v105, v105
	v_max_f32_e32 v137, v104, v104
	v_max_f32_e32 v136, v137, v136
	v_max3_f32 v134, v134, v135, v136
	v_max_f32_e32 v135, v99, v99
	v_max_f32_e32 v136, v98, v98
	v_mfma_f32_16x16x32_bf16 v[156:159], v[232:235], v[22:25], v[122:125]
	v_max_f32_e32 v135, v136, v135
	v_max_f32_e32 v136, v101, v101
	v_max_f32_e32 v137, v100, v100
	s_waitcnt lgkmcnt(2)
; #define MFMA16(a, b, c) __builtin_amdgcn_mfma_f32_16x16x32_bf16((a), (b), (c), 0, 0, 0)
; __device__ __forceinline__ void attn_phase(LAS unsigned char* lds, const bf16_t* PROJ, const bf16_t* KM, const bf16_t* VT, bf16_t* Y, float* SS, int bx, int G, int tid) {
;     ...
;                     for (int i = 0; i < 4; ++i) st[4 * c + i] = MFMA16(kfb[ks % 3][i], qf[ks], st[4 * c + i]);
;                 }
;                 if (c == 3) {
;                     float mx = -3.0e38f;
; #pragma unroll
;                     for (int i = 0; i < 16; ++i) mx = fmaxf(fmaxf(mx, fmaxf(st[i][0], st[i][1])), fmaxf(st[i][2], st[i][3]));
;                     mx = fmaxf(mx, __shfl_xor(mx, 16)); mx = fmaxf(mx, __shfl_xor(mx, 32));
;                     float l = 0.f;
; #pragma unroll
;                     for (int i = 0; i < 16; ++i)
; #pragma unroll
;                         for (int e = 0; e < 4; ++e) { const float p = __builtin_amdgcn_exp2f(st[i][e] - mx); st[i][e] = p; l += p; }
;                     l += __shfl_xor(l, 16); l += __shfl_xor(l, 32); linv = 1.0f / l;
	v_mfma_f32_16x16x32_bf16 v[122:125], v[138:141], v[26:29], v[118:121]
	v_max_f32_e32 v136, v137, v136
	v_max3_f32 v134, v134, v135, v136
	v_max_f32_e32 v135, v127, v127
	v_max_f32_e32 v136, v126, v126
	v_max_f32_e32 v135, v136, v135
	v_max_f32_e32 v136, v129, v129
	v_max_f32_e32 v137, v128, v128
	s_waitcnt lgkmcnt(1)
	v_mfma_f32_16x16x32_bf16 v[118:121], v[142:145], v[26:29], v[156:159]
	v_max_f32_e32 v136, v137, v136
	v_max3_f32 v134, v134, v135, v136
	v_max_f32_e32 v135, v123, v123
	v_max_f32_e32 v136, v122, v122
	v_max_f32_e32 v135, v136, v135
	v_max_f32_e32 v136, v125, v125
	v_max_f32_e32 v137, v124, v124
	s_waitcnt lgkmcnt(0)
	v_mfma_f32_16x16x32_bf16 v[114:117], v[152:155], v[26:29], v[170:173]
	v_max_f32_e32 v136, v137, v136
	v_max3_f32 v134, v134, v135, v136
	v_max_f32_e32 v135, v119, v119
	v_max_f32_e32 v136, v118, v118
	v_max_f32_e32 v135, v136, v135
	v_max_f32_e32 v136, v121, v121
	v_max_f32_e32 v137, v120, v120
	v_max_f32_e32 v136, v137, v136
	v_max3_f32 v134, v134, v135, v136
	v_max_f32_e32 v135, v115, v115
	v_max_f32_e32 v136, v114, v114
	v_max_f32_e32 v135, v136, v135
	v_max_f32_e32 v136, v117, v117
	v_max_f32_e32 v137, v116, v116
	v_max_f32_e32 v136, v137, v136
	v_max3_f32 v134, v134, v135, v136
	ds_bpermute_b32 v135, v215, v134
	s_waitcnt lgkmcnt(0)
	v_max_f32_e32 v135, v135, v135
	v_max_f32_e32 v134, v134, v135
	ds_bpermute_b32 v135, v216, v134
	s_waitcnt lgkmcnt(0)
	v_max_f32_e32 v135, v135, v135
	v_max_f32_e32 v134, v134, v135
	v_sub_f32_e32 v62, v62, v134
	v_exp_f32_e32 v62, v62
	v_sub_f32_e32 v63, v63, v134
	v_exp_f32_e32 v63, v63
	v_sub_f32_e32 v64, v64, v134
	v_exp_f32_e32 v64, v64
	v_sub_f32_e32 v65, v65, v134
	v_exp_f32_e32 v65, v65
	v_sub_f32_e32 v58, v58, v134
	v_add_f32_e32 v135, 0, v62
	v_exp_f32_e32 v58, v58
	v_sub_f32_e32 v59, v59, v134
	v_add_f32_e32 v135, v63, v135
	v_exp_f32_e32 v59, v59
	v_sub_f32_e32 v60, v60, v134
	v_add_f32_e32 v135, v64, v135
	v_exp_f32_e32 v60, v60
	v_sub_f32_e32 v61, v61, v134
	v_add_f32_e32 v135, v65, v135
	v_exp_f32_e32 v61, v61
	v_sub_f32_e32 v54, v54, v134
	v_add_f32_e32 v135, v58, v135
	v_exp_f32_e32 v54, v54
	v_sub_f32_e32 v55, v55, v134
	v_add_f32_e32 v135, v59, v135
	v_exp_f32_e32 v55, v55
	v_sub_f32_e32 v56, v56, v134
	v_add_f32_e32 v135, v60, v135
	v_exp_f32_e32 v56, v56
	v_sub_f32_e32 v57, v57, v134
	v_add_f32_e32 v135, v61, v135
	v_exp_f32_e32 v57, v57
	v_sub_f32_e32 v42, v42, v134
	v_add_f32_e32 v135, v54, v135
	v_exp_f32_e32 v42, v42
	v_sub_f32_e32 v43, v43, v134
	v_add_f32_e32 v135, v55, v135
	v_exp_f32_e32 v43, v43
	v_sub_f32_e32 v44, v44, v134
	v_add_f32_e32 v135, v56, v135
	v_exp_f32_e32 v44, v44
	v_sub_f32_e32 v45, v45, v134
	v_add_f32_e32 v135, v57, v135
	v_exp_f32_e32 v45, v45
	v_sub_f32_e32 v94, v94, v134
	v_add_f32_e32 v135, v42, v135
	v_exp_f32_e32 v94, v94
	v_sub_f32_e32 v95, v95, v134
	v_add_f32_e32 v135, v43, v135
	v_exp_f32_e32 v95, v95
	v_sub_f32_e32 v96, v96, v134
	v_add_f32_e32 v135, v44, v135
	v_exp_f32_e32 v96, v96
	v_sub_f32_e32 v97, v97, v134
	v_add_f32_e32 v135, v45, v135
	v_exp_f32_e32 v97, v97
	v_sub_f32_e32 v90, v90, v134
	v_add_f32_e32 v135, v94, v135
	v_exp_f32_e32 v90, v90
	v_sub_f32_e32 v91, v91, v134
	v_add_f32_e32 v135, v95, v135
	v_exp_f32_e32 v91, v91
	v_sub_f32_e32 v92, v92, v134
	v_add_f32_e32 v135, v96, v135
	v_exp_f32_e32 v92, v92
	v_sub_f32_e32 v93, v93, v134
	v_add_f32_e32 v135, v97, v135
	v_exp_f32_e32 v93, v93
	v_sub_f32_e32 v86, v86, v134
	v_add_f32_e32 v135, v90, v135
	v_exp_f32_e32 v86, v86
	v_sub_f32_e32 v87, v87, v134
	v_add_f32_e32 v135, v91, v135
	v_exp_f32_e32 v87, v87
	v_sub_f32_e32 v88, v88, v134
	v_add_f32_e32 v135, v92, v135
	v_exp_f32_e32 v88, v88
	v_sub_f32_e32 v89, v89, v134
	v_add_f32_e32 v135, v93, v135
	v_exp_f32_e32 v89, v89
	v_sub_f32_e32 v78, v78, v134
	v_add_f32_e32 v135, v86, v135
	v_exp_f32_e32 v78, v78
	v_sub_f32_e32 v79, v79, v134
	v_add_f32_e32 v135, v87, v135
	v_exp_f32_e32 v79, v79
	v_sub_f32_e32 v80, v80, v134
	v_add_f32_e32 v135, v88, v135
	v_exp_f32_e32 v80, v80
	v_sub_f32_e32 v81, v81, v134
	v_add_f32_e32 v135, v89, v135
	v_exp_f32_e32 v81, v81
	v_sub_f32_e32 v110, v110, v134
	v_add_f32_e32 v135, v78, v135
	v_exp_f32_e32 v110, v110
	v_sub_f32_e32 v111, v111, v134
	v_add_f32_e32 v135, v79, v135
	v_exp_f32_e32 v111, v111
	v_sub_f32_e32 v112, v112, v134
	v_add_f32_e32 v135, v80, v135
	v_exp_f32_e32 v112, v112
	v_sub_f32_e32 v113, v113, v134
	v_add_f32_e32 v135, v81, v135
	v_exp_f32_e32 v113, v113
	v_sub_f32_e32 v106, v106, v134
	v_add_f32_e32 v135, v110, v135
	v_exp_f32_e32 v106, v106
	v_sub_f32_e32 v107, v107, v134
	v_add_f32_e32 v135, v111, v135
	v_exp_f32_e32 v107, v107
	v_sub_f32_e32 v108, v108, v134
	v_add_f32_e32 v135, v112, v135
	v_exp_f32_e32 v108, v108
	v_sub_f32_e32 v109, v109, v134
	v_add_f32_e32 v135, v113, v135
	v_exp_f32_e32 v109, v109
	v_sub_f32_e32 v102, v102, v134
	v_add_f32_e32 v135, v106, v135
	v_exp_f32_e32 v102, v102
	v_sub_f32_e32 v103, v103, v134
	v_add_f32_e32 v135, v107, v135
	v_exp_f32_e32 v103, v103
	v_sub_f32_e32 v104, v104, v134
	v_add_f32_e32 v135, v108, v135
	v_exp_f32_e32 v104, v104
	v_sub_f32_e32 v105, v105, v134
	v_add_f32_e32 v135, v109, v135
	v_exp_f32_e32 v105, v105
	v_sub_f32_e32 v98, v98, v134
	v_add_f32_e32 v135, v102, v135
	v_exp_f32_e32 v136, v98
	v_add_f32_e32 v135, v103, v135
	v_add_f32_e32 v135, v104, v135
	v_add_f32_e32 v135, v105, v135
	v_sub_f32_e32 v99, v99, v134
	v_add_f32_e32 v98, v136, v135
	v_exp_f32_e32 v135, v99
	v_sub_f32_e32 v99, v100, v134
	v_exp_f32_e32 v137, v99
	v_sub_f32_e32 v99, v101, v134
; __device__ __forceinline__ unsigned cvt_pk_bf16(float lo, float hi) { unsigned r; asm volatile("v_cvt_pk_bf16_f32 %0, %1, %2" : "=v"(r) : "v"(lo), "v"(hi)); return r; }
; __device__ __forceinline__ void attn_phase(LAS unsigned char* lds, const bf16_t* PROJ, const bf16_t* KM, const bf16_t* VT, bf16_t* Y, float* SS, int bx, int G, int tid) {
;     ...
;             if (c == 4) {
;                 const bf16_t* gp = PJ(PROJ, tok, COL_GC + h * 256 + 8 * fq);
; #pragma unroll
;                 for (int i = 0; i < 16; ++i) ot[i] = (f32x4){0.f, 0.f, 0.f, 0.f};
; #pragma unroll
;                 for (int p = 0; p < 8; ++p) gt[p] = *(const u32x4*)(gp + 512 * p);
;                 if (has_next) { const bf16_t* qp = PJ(PROJ, T0n + wid * 16 + fr, COL_Q + hn * 256 + fq * 8);
; #pragma unroll
;                     for (int ks = 0; ks < 8; ++ks) qf[ks] = *(const bf16x8*)(qp + ks * 512); }
;     ...
;                     for (int i = 0; i < 16; ++i)
; #pragma unroll
;                         for (int e = 0; e < 4; ++e) { const float p = __builtin_amdgcn_exp2f(st[i][e] - mx); st[i][e] = p; l += p; }
;                     l += __shfl_xor(l, 16); l += __shfl_xor(l, 32); linv = 1.0f / l;
; #pragma unroll
;                     for (int kk = 0; kk < 8; ++kk) { u32x4 w; w.x = cvt_pk_bf16(st[2 * kk][0], st[2 * kk][1]); w.y = cvt_pk_bf16(st[2 * kk][2], st[2 * kk][3]);
;                         w.z = cvt_pk_bf16(st[2 * kk + 1][0], st[2 * kk + 1][1]); w.w = cvt_pk_bf16(st[2 * kk + 1][2], st[2 * kk + 1][3]); pf[kk] = __builtin_bit_cast(bf16x8, w); }
;                 }
	v_exp_f32_e32 v101, v99
	v_sub_f32_e32 v99, v126, v134
	v_exp_f32_e32 v138, v99
	v_sub_f32_e32 v99, v127, v134
	v_add_f32_e32 v98, v135, v98
	v_exp_f32_e32 v139, v99
	v_sub_f32_e32 v99, v128, v134
	v_add_f32_e32 v98, v137, v98
	v_exp_f32_e32 v140, v99
	v_sub_f32_e32 v99, v129, v134
	v_add_f32_e32 v98, v101, v98
	v_exp_f32_e32 v141, v99
	v_sub_f32_e32 v99, v122, v134
	v_add_f32_e32 v98, v138, v98
	v_exp_f32_e32 v142, v99
	v_sub_f32_e32 v99, v123, v134
	v_add_f32_e32 v98, v139, v98
	v_exp_f32_e32 v143, v99
	v_sub_f32_e32 v99, v124, v134
	v_add_f32_e32 v98, v140, v98
	v_exp_f32_e32 v144, v99
	v_sub_f32_e32 v99, v125, v134
	v_add_f32_e32 v98, v141, v98
	v_exp_f32_e32 v145, v99
	v_sub_f32_e32 v99, v118, v134
	v_add_f32_e32 v98, v142, v98
	v_exp_f32_e32 v152, v99
	v_sub_f32_e32 v99, v119, v134
	v_add_f32_e32 v98, v143, v98
	v_exp_f32_e32 v153, v99
	v_sub_f32_e32 v99, v120, v134
	v_add_f32_e32 v98, v144, v98
	v_exp_f32_e32 v154, v99
	v_sub_f32_e32 v99, v121, v134
	v_add_f32_e32 v98, v145, v98
	v_exp_f32_e32 v155, v99
	v_sub_f32_e32 v99, v114, v134
	v_add_f32_e32 v98, v152, v98
	v_exp_f32_e32 v156, v99
	v_sub_f32_e32 v99, v115, v134
	v_add_f32_e32 v98, v153, v98
	v_exp_f32_e32 v157, v99
	v_sub_f32_e32 v99, v116, v134
	v_add_f32_e32 v98, v154, v98
	v_exp_f32_e32 v158, v99
	v_sub_f32_e32 v99, v117, v134
	v_add_f32_e32 v98, v155, v98
	v_exp_f32_e32 v134, v99
	v_add_f32_e32 v98, v156, v98
	v_add_f32_e32 v98, v157, v98
	v_add_f32_e32 v98, v158, v98
	v_add_f32_e32 v98, v134, v98
	ds_bpermute_b32 v99, v215, v98
	v_cvt_pk_bf16_f32 v126, v62, v63
	v_cvt_pk_bf16_f32 v127, v64, v65
	v_cvt_pk_bf16_f32 v128, v58, v59
	v_cvt_pk_bf16_f32 v129, v60, v61
	v_cvt_pk_bf16_f32 v122, v54, v55
	v_cvt_pk_bf16_f32 v123, v56, v57
	v_cvt_pk_bf16_f32 v124, v42, v43
	v_add_co_u32_e32 v42, vcc, s71, v146
	s_waitcnt lgkmcnt(0)
	v_add_f32_e32 v223, v98, v99
	v_cvt_pk_bf16_f32 v125, v44, v45
	v_cvt_pk_bf16_f32 v118, v94, v95
	v_cvt_pk_bf16_f32 v119, v96, v97
	v_cvt_pk_bf16_f32 v120, v90, v91
	v_cvt_pk_bf16_f32 v121, v92, v93
	v_cvt_pk_bf16_f32 v114, v86, v87
	v_cvt_pk_bf16_f32 v115, v88, v89
	v_cvt_pk_bf16_f32 v116, v78, v79
	v_cvt_pk_bf16_f32 v117, v80, v81
	v_cvt_pk_bf16_f32 v110, v110, v111
	v_cvt_pk_bf16_f32 v111, v112, v113
	v_cvt_pk_bf16_f32 v112, v106, v107
	v_cvt_pk_bf16_f32 v113, v108, v109
	v_cvt_pk_bf16_f32 v98, v102, v103
	v_cvt_pk_bf16_f32 v99, v104, v105
	v_cvt_pk_bf16_f32 v100, v136, v135
	v_cvt_pk_bf16_f32 v101, v137, v101
	v_cvt_pk_bf16_f32 v86, v138, v139
	v_cvt_pk_bf16_f32 v87, v140, v141
	v_cvt_pk_bf16_f32 v88, v142, v143
	v_cvt_pk_bf16_f32 v89, v144, v145
	v_cvt_pk_bf16_f32 v78, v152, v153
	v_add_u32_e32 v142, 0, v196
	v_add_u32_e32 v143, 0, v207
	v_add_u32_e32 v144, 0, v208
	v_add_u32_e32 v145, 0, v210
	v_add_u32_e32 v152, 0, v214
	v_addc_co_u32_e32 v43, vcc, 0, v147, vcc
	v_cvt_pk_bf16_f32 v79, v154, v155
	v_cvt_pk_bf16_f32 v80, v156, v157
	v_cvt_pk_bf16_f32 v81, v158, v134
	s_waitcnt vmcnt(7)
	ds_write_b64 v142, v[82:83]
	ds_write_b64 v143, v[84:85]
	s_waitcnt vmcnt(6)
	ds_write_b64 v144, v[74:75] offset:4096
	ds_write_b64 v145, v[76:77]
	s_waitcnt vmcnt(5)
	ds_write_b64 v142, v[70:71] offset:16384
	ds_write_b64 v143, v[72:73] offset:16384
	s_waitcnt vmcnt(4)
	ds_write_b64 v144, v[66:67] offset:20480
	ds_write_b64 v152, v[68:69]
	s_waitcnt lgkmcnt(0)
	s_barrier
	global_load_dwordx4 v[90:93], v[42:43], off
	v_add_co_u32_e32 v42, vcc, s72, v146
	ds_bpermute_b32 v224, v216, v223
	s_nop 0
	v_addc_co_u32_e32 v43, vcc, 0, v147, vcc
	global_load_dwordx4 v[94:97], v[42:43], off
	v_add_co_u32_e32 v42, vcc, s73, v146
	s_nop 1
	v_addc_co_u32_e32 v43, vcc, 0, v147, vcc
	global_load_dwordx4 v[102:105], v[42:43], off
	v_add_co_u32_e32 v42, vcc, s75, v146
	s_nop 1
	v_addc_co_u32_e32 v43, vcc, 0, v147, vcc
	global_load_dwordx4 v[106:109], v[42:43], off
	v_add_co_u32_e32 v42, vcc, s89, v130
	s_nop 1
	v_addc_co_u32_e32 v43, vcc, 0, v131, vcc
	global_load_dwordx4 v[82:85], v[42:43], off
	global_load_dwordx4 v[74:77], v[132:133], off offset:1024
	global_load_dwordx4 v[70:73], v[132:133], off offset:2048
	global_load_dwordx4 v[66:69], v[132:133], off offset:3072
	v_add_co_u32_e32 v42, vcc, 0xc001000, v130
	s_nop 1
	v_addc_co_u32_e32 v43, vcc, 0, v131, vcc
	global_load_dwordx4 v[62:65], v[42:43], off
	global_load_dwordx4 v[58:61], v[42:43], off offset:1024
	global_load_dwordx4 v[54:57], v[42:43], off offset:2048
	s_nop 0
	global_load_dwordx4 v[42:45], v[42:43], off offset:3072
	s_and_b64 vcc, exec, s[16:17]
	s_cbranch_vccnz .LBB0_451
	s_lshl_b32 s4, s93, 23
	s_add_u32 s96, s36, s4
	s_addc_u32 s97, s37, 0
	s_add_i32 s4, s92, s80
	s_ashr_i32 s4, s4, 4
	s_ashr_i32 s5, s4, 31
	s_lshl_b64 s[4:5], s[4:5], 13
	s_add_u32 s4, s96, s4
	s_addc_u32 s5, s97, s5
	v_mov_b32_e32 v2, v189
	v_mov_b32_e32 v189, v179
	v_lshl_add_u64 v[14:15], s[4:5], 0, v[188:189]
	v_add_co_u32_e32 v12, vcc, 0xa000000, v14
	v_lshl_add_u64 v[10:11], v[14:15], 0, s[10:11]
	s_nop 0
	v_addc_co_u32_e32 v13, vcc, 0, v15, vcc
	v_add_co_u32_e32 v26, vcc, 0xa001000, v14
	v_mov_b32_e32 v189, v2
	s_nop 0
	v_addc_co_u32_e32 v27, vcc, 0, v15, vcc
	global_load_dwordx4 v[2:5], v[10:11], off offset:1024
	global_load_dwordx4 v[6:9], v[10:11], off offset:2048
	global_load_dwordx4 v[30:33], v[12:13], off
	s_nop 0
	global_load_dwordx4 v[10:13], v[10:11], off offset:3072
	s_nop 0
	global_load_dwordx4 v[14:17], v[26:27], off
	global_load_dwordx4 v[18:21], v[26:27], off offset:1024
	global_load_dwordx4 v[22:25], v[26:27], off offset:2048
	s_nop 0
	global_load_dwordx4 v[26:29], v[26:27], off offset:3072

; #define LAS __attribute__((address_space(3)))
; __device__ __forceinline__ void pool_phase(LAS unsigned char* lds, const bf16_t* PROJ, const bf16_t* PW, const float* pscale, bf16_t* Y, float* SS, int bx, int G) {
;     int tid_ = threadIdx.x; asm volatile("" : "+v"(tid_));
;     const int tid = tid_, lane = tid & 63, wid = __builtin_amdgcn_readfirstlane(tid >> 6), fr = lane & 15, fq = lane >> 4;
;     const int g = bx & 3, step = G >> 2; int pt = bx >> 2;
;     if (step == 0 || bx >= 4 * step || pt >= 256) return;
;     bf16x8 wf[2][8];
; #pragma unroll
;     for (int j = 0; j < 2; ++j)
; #pragma unroll
;         for (int ks = 0; ks < 8; ++ks) wf[j][ks] = *(const bf16x8*)(PW + (size_t)(g * 256 + 32 * wid + 8 * (fr >> 2) + 4 * j + (fr & 3)) * 256 + 32 * ks + 8 * fq);
;     u32x4 stg[5]; u32x4 gt[4];
;     ...
;     POOL_LOAD(pt);
;     const int cp = tid & 127, tb = tid >> 7, w = 2 << g, t_start = 16 * tb;
;     const LAS unsigned* xs = (const LAS unsigned*)(lds + PL_XS) + cp;
.LBB0_459:
	v_mov_b32_e32 v1, s85
	ds_read_b32 v2, v1 offset:8
	ds_read_b32 v1, v1 offset:12
	s_waitcnt lgkmcnt(0)
	v_readfirstlane_b32 s0, v2
	v_readfirstlane_b32 s1, v1
	s_nop 3
	s_movk_i32 m0, 0xff
	s_cmp_eq_u32 s1, 0
	s_cbranch_scc0 .Lp2v_b
	s_and_b32 s4, s0, 7
	s_lshl_b32 s5, s4, 7
	s_lshr_b32 s0, s0, 3
	s_add_i32 s2, s5, s0
	s_movk_i32 s3, 32
	s_lshl_b32 s4, s4, 5
	s_add_i32 m0, s4, 31
.Lp2v_b:
	s_ashr_i32 s86, s2, 2
	s_cmp_lt_u32 s3, 4
	s_cselect_b64 s[0:1], -1, 0
	s_and_b32 s75, s3, -4
	s_cmp_ge_i32 s2, s75
	s_cselect_b64 s[4:5], -1, 0
	s_cmp_eq_u32 s3, 32
	s_cselect_b64 s[4:5], 0, s[4:5]
	s_cmp_gt_i32 s86, m0
	s_cselect_b64 s[10:11], -1, 0
	s_or_b64 s[4:5], s[10:11], s[4:5]
	v_mov_b32_e32 v88, v0
	s_or_b64 s[0:1], s[0:1], s[4:5]
	s_and_b64 vcc, exec, s[0:1]
	v_readfirstlane_b32 s18, v88
	s_cbranch_vccnz .LBB0_630
	s_ashr_i32 s17, s18, 6
	s_lshl_b32 s0, s74, 8
	s_lshl_b32 s76, s86, 6
	s_and_b32 s1, s2, 0xfc
	s_cmp_eq_u32 s1, 0
	s_cselect_b64 s[10:11], -1, 0
	s_lshl_b32 s16, s17, 5
	v_lshlrev_b32_e32 v1, 1, v88
	s_add_i32 s16, s16, s0
	v_and_b32_e32 v1, 24, v1
	v_and_b32_e32 v2, 3, v88
	v_bfe_u32 v90, v88, 4, 2
	s_waitcnt vmcnt(0)
	v_or3_b32 v34, v1, v2, s16
	v_mov_b32_e32 v66, 0
	v_lshlrev_b32_e32 v2, 4, v90
	v_mov_b32_e32 v3, v66
	v_ashrrev_i32_e32 v35, 31, v34
	v_lshl_add_u64 v[36:37], s[8:9], 0, v[2:3]
	v_lshlrev_b64 v[2:3], 9, v[34:35]
	v_or_b32_e32 v34, 4, v34
	v_ashrrev_i32_e32 v35, 31, v34
	v_lshlrev_b64 v[34:35], 9, v[34:35]
	v_lshl_add_u64 v[30:31], v[36:37], 0, v[2:3]
	v_lshl_add_u64 v[62:63], v[36:37], 0, v[34:35]
	s_waitcnt lgkmcnt(0)
	global_load_dwordx4 v[2:5], v[30:31], off
	global_load_dwordx4 v[6:9], v[30:31], off offset:64
	global_load_dwordx4 v[10:13], v[30:31], off offset:128
	global_load_dwordx4 v[14:17], v[30:31], off offset:192
	global_load_dwordx4 v[18:21], v[30:31], off offset:256
	global_load_dwordx4 v[22:25], v[30:31], off offset:320
	global_load_dwordx4 v[26:29], v[30:31], off offset:384
	s_nop 0
	global_load_dwordx4 v[30:33], v[30:31], off offset:448
	s_nop 0
	global_load_dwordx4 v[34:37], v[62:63], off
	global_load_dwordx4 v[38:41], v[62:63], off offset:64
	global_load_dwordx4 v[42:45], v[62:63], off offset:128
	global_load_dwordx4 v[46:49], v[62:63], off offset:192
	global_load_dwordx4 v[50:53], v[62:63], off offset:256
	global_load_dwordx4 v[54:57], v[62:63], off offset:320
	global_load_dwordx4 v[58:61], v[62:63], off offset:384
	s_nop 0
	global_load_dwordx4 v[62:65], v[62:63], off offset:448
	v_lshlrev_b32_e32 v86, 4, v88
	v_bfe_u32 v89, v88, 2, 4
	v_and_b32_e32 v1, 0x1c30, v86
	v_lshrrev_b32_e32 v67, 2, v88
	v_lshl_or_b32 v68, v89, 6, v1
	v_ashrrev_i32_e32 v1, 5, v88
	v_bfi_b32 v91, -16, v1, v67
	v_cmp_gt_i32_e64 s[0:1], 16, v91
	v_mov_b32_e32 v69, v66
	s_and_b64 s[4:5], s[10:11], s[0:1]
	s_add_i32 s12, s76, -16
	v_lshl_add_u64 v[130:131], s[6:7], 0, v[68:69]
	s_xor_b64 s[6:7], s[4:5], -1
	v_mov_b32_e32 v70, 0
	v_mov_b32_e32 v71, 0
	v_mov_b32_e32 v72, 0
	v_mov_b32_e32 v73, 0
	s_and_saveexec_b64 s[4:5], s[6:7]
	s_cbranch_execz .LBB0_462
	v_add_u32_e32 v67, s12, v1
	v_ashrrev_i32_e32 v68, 4, v67
	v_ashrrev_i32_e32 v69, 31, v68
	v_lshlrev_b64 v[68:69], 13, v[68:69]
	v_lshl_add_u64 v[68:69], v[130:131], 0, v[68:69]
	global_load_dwordx4 v[70:73], v[68:69], off

; #define LAS __attribute__((address_space(3)))
; __device__ __forceinline__ void pool_phase(LAS unsigned char* lds, const bf16_t* PROJ, const bf16_t* PW, const float* pscale, bf16_t* Y, float* SS, int bx, int G) {
;     ...
;     for (; pt < 256; pt += step) {
;         const int T0 = pt * 64, pos0 = T0 % SEQ;
; #pragma unroll
;         for (int it = 0; it < 5; ++it) { const int p = tid + 512 * it, sb_ = p >> 6, row = 16 * (sb_ >> 3) + ((p >> 2) & 15), c16 = 4 * (sb_ & 7) + (p & 3); *(LAS u32x4*)(lds + PL_XS + row * 512 + c16 * 16) = stg[it]; }
; #pragma unroll
;         for (int m = 0; m < 4; ++m) gt[m] = *(const u32x4*)PJ(PROJ, T0 + 16 * m + fr, COL_GA + g * 256 + 32 * wid + 8 * fq);
;         __syncthreads();
;         if (pt + step < 256) POOL_LOAD(pt + step);
.LBB0_472:
	s_add_i32 s62, s60, -3
	s_ashr_i32 s63, s62, 31
	s_lshl_b64 s[62:63], s[62:63], 13
	v_lshl_add_u64 v[86:87], v[132:133], 0, s[62:63]
	s_add_i32 s62, s60, -2
	s_ashr_i32 s63, s62, 31
	s_lshl_b64 s[62:63], s[62:63], 13
	v_lshl_add_u64 v[88:89], v[132:133], 0, s[62:63]
	s_add_i32 s62, s60, -1
	s_ashr_i32 s63, s62, 31
	s_lshl_b64 s[62:63], s[62:63], 13
	s_ashr_i32 s61, s60, 31
	global_load_dwordx4 v[98:101], v[86:87], off
	global_load_dwordx4 v[94:97], v[88:89], off
	v_lshl_add_u64 v[86:87], v[132:133], 0, s[62:63]
	s_lshl_b64 s[62:63], s[60:61], 13
	v_lshl_add_u64 v[88:89], v[132:133], 0, s[62:63]
	global_load_dwordx4 v[90:93], v[86:87], off
	s_nop 0
	global_load_dwordx4 v[86:89], v[88:89], off
	s_add_i32 s61, s86, s77
	s_cmp_gt_i32 s61, m0
	s_cselect_b64 s[62:63], -1, 0
	s_and_b64 vcc, exec, s[62:63]
	s_waitcnt vmcnt(4)
	ds_write_b128 v183, v[70:73]
	ds_write_b128 v184, v[66:69]
	ds_write_b128 v185, v[74:77]
	ds_write_b128 v186, v[78:81]
	ds_write_b128 v187, v[82:85]
	s_waitcnt lgkmcnt(0)
	s_barrier
	s_cbranch_vccnz .LBB0_484
	s_and_b32 s70, s61, 63
	s_cmp_eq_u32 s70, 0
	s_cselect_b64 s[70:71], -1, 0
	s_and_b64 s[72:73], s[70:71], s[0:1]
	s_xor_b64 s[88:89], s[72:73], -1
	v_mov_b32_e32 v74, 0
	v_mov_b32_e32 v70, 0
	v_mov_b32_e32 v71, 0
	v_mov_b32_e32 v72, 0
	v_mov_b32_e32 v73, 0
	s_and_saveexec_b64 s[72:73], s[88:89]
	s_cbranch_execz .LBB0_475
	v_add_u32_e32 v66, s79, v179
	v_ashrrev_i32_e32 v66, 4, v66
	v_ashrrev_i32_e32 v67, 31, v66
	v_lshlrev_b64 v[66:67], 13, v[66:67]
	v_lshl_add_u64 v[66:67], v[130:131], 0, v[66:67]
	global_load_dwordx4 v[70:73], v[66:67], off

; #define LAS __attribute__((address_space(3)))
; __device__ __forceinline__ void sgu_phase(LAS unsigned char* lds, const bf16_t* PROJ, const float* VST, const bf16_t* SW, const float* ln_g, const float* ln_b, const float* sgu_b,
;                                           bf16_t* Y, float* SS, int bx, int G) {
;     int tid_ = threadIdx.x; asm volatile("" : "+v"(tid_));
;     const int tid = tid_, lane = tid & 63, wid = __builtin_amdgcn_readfirstlane(tid >> 6), fr = lane & 15, fq = lane >> 4;
;     const int h = bx & 7, step = G >> 3; int cc = bx >> 3;
;     if (step == 0 || bx >= 8 * step || cc >= 128) return;
;     LAS float* meanp = (LAS float*)(lds + SG_MEAN); LAS float* rstdp = (LAS float*)(lds + SG_RSTD); LAS float* ssw = (LAS float*)(lds + SG_SSW);
; #pragma unroll
;     for (int it = 0; it < 4; ++it) { const int p = tid + 512 * it, row = p >> 4, c16 = p & 15;
;         *(LAS u32x4*)(lds + SG_W + row * SG_ROWB + c16 * 16) = *(const u32x4*)(SW + (size_t)(h * 128 + row) * 128 + c16 * 8); }
;     const int dch = tid & 127; const float gch = ln_g[h * 128 + dch], bch = ln_b[h * 128 + dch];
;     const int dp = wid >> 1, th = wid & 1;
;     float bias[4];
; #pragma unroll
;     for (int jj = 0; jj < 4; ++jj) bias[jj] = sgu_b[h * 128 + 16 * (4 * th + jj) + fr];
;     u32x4 vst[4]; f32x4 sp[2];
;     ...
;     SGU_LOAD(cc);
.LBB0_630:
	v_mov_b32_e32 v1, s85
	ds_read_b32 v2, v1 offset:8
	ds_read_b32 v1, v1 offset:12
	s_waitcnt lgkmcnt(0)
	v_readfirstlane_b32 s0, v2
	v_readfirstlane_b32 s1, v1
	s_nop 3
	s_movk_i32 m0, 0x7f
	s_cmp_eq_u32 s1, 0
	s_cbranch_scc0 .Lp2v_c
	s_and_b32 s4, s0, 7
	s_lshl_b32 s4, s4, 4
	s_add_i32 m0, s4, 15
.Lp2v_c:
	s_ashr_i32 s20, s2, 3
	s_cmp_lt_u32 s3, 8
	s_cselect_b64 s[0:1], -1, 0
	s_and_b32 s4, s3, -8
	s_cmp_ge_i32 s2, s4
	s_cselect_b64 s[4:5], -1, 0
	s_cmp_eq_u32 s3, 32
	s_cselect_b64 s[4:5], 0, s[4:5]
	s_cmp_gt_i32 s20, m0
	s_cselect_b64 s[6:7], -1, 0
	s_or_b64 s[4:5], s[6:7], s[4:5]
	v_mov_b32_e32 v26, v0
	s_or_b64 s[0:1], s[0:1], s[4:5]
	v_ashrrev_i32_e32 v27, 6, v26
	s_and_b64 vcc, exec, s[0:1]
	v_readfirstlane_b32 s7, v27
	s_cbranch_vccnz .LBB0_664
	s_and_b32 s6, s2, 7
	s_lshl_b32 s4, s6, 7
	v_ashrrev_i32_e32 v31, 4, v26
	v_and_b32_e32 v30, 15, v26
	v_add_u32_e32 v2, s4, v31
	v_lshlrev_b32_e32 v98, 4, v30
	v_mov_b32_e32 v99, 0
	v_ashrrev_i32_e32 v3, 31, v2
	v_add_u32_e32 v1, 0x200, v26
	v_lshl_add_u64 v[10:11], s[68:69], 0, v[98:99]
	v_lshlrev_b64 v[2:3], 8, v[2:3]
	v_ashrrev_i32_e32 v32, 4, v1
	v_lshl_add_u64 v[12:13], v[10:11], 0, v[2:3]
	v_add_u32_e32 v2, s4, v32
	v_ashrrev_i32_e32 v3, 31, v2
	v_add_u32_e32 v1, 0x400, v26
	v_lshlrev_b64 v[2:3], 8, v[2:3]
	v_ashrrev_i32_e32 v33, 4, v1
	v_lshl_add_u64 v[14:15], v[10:11], 0, v[2:3]
	s_waitcnt lgkmcnt(0)
	global_load_dwordx4 v[2:5], v[12:13], off
	global_load_dwordx4 v[6:9], v[14:15], off
	v_add_u32_e32 v12, s4, v33
	v_ashrrev_i32_e32 v13, 31, v12
	v_add_u32_e32 v1, 0x600, v26
	v_lshlrev_b64 v[12:13], 8, v[12:13]
	s_waitcnt vmcnt(0)
	v_ashrrev_i32_e32 v34, 4, v1
	v_lshl_add_u64 v[18:19], v[10:11], 0, v[12:13]
	v_add_u32_e32 v12, s4, v34
	v_ashrrev_i32_e32 v13, 31, v12
	v_lshlrev_b64 v[12:13], 8, v[12:13]
	v_lshl_add_u64 v[20:21], v[10:11], 0, v[12:13]
	global_load_dwordx4 v[10:13], v[18:19], off
	global_load_dwordx4 v[14:17], v[20:21], off
	s_lshl_b32 s5, s2, 22
	s_ashr_i32 s21, s3, 3
	v_lshrrev_b32_e32 v1, 4, v26
	v_and_b32_e32 v37, 3, v26
	s_and_b32 s5, s5, 0x1800000
	v_and_b32_e32 v36, 0x7f, v26
	v_lshlrev_b32_e32 v18, 3, v26
	v_and_or_b32 v1, v1, 12, v37
	s_add_u32 s8, s36, s5
	v_and_b32_e32 v28, 0x1e0, v18
	v_or_b32_e32 v18, s4, v36
	v_lshlrev_b32_e32 v1, 3, v1
	s_addc_u32 s9, s37, 0
	s_add_i32 s13, 0, 0x11000
	s_movk_i32 s12, 0x110
	v_lshlrev_b32_e32 v19, 2, v18
	s_and_b32 s17, s7, 1
	v_or_b32_e32 v20, s4, v1
	v_add_u32_e32 v18, s13, v98
	v_or_b32_e32 v29, s4, v30
	v_and_b32_e32 v39, 24, v1
	global_load_dword v1, v19, s[64:65]
	global_load_dword v108, v19, s[66:67]
	s_lshl_b32 s18, s17, 6
	v_lshlrev_b32_e32 v40, 4, v20
	v_mad_u64_u32 v[20:21], s[10:11], v31, s12, v[18:19]
	v_mad_u64_u32 v[22:23], s[10:11], v32, s12, v[18:19]
	v_mad_u64_u32 v[24:25], s[10:11], v33, s12, v[18:19]
	v_mad_u64_u32 v[18:19], s[10:11], v34, s12, v[18:19]
	v_or_b32_e32 v19, s18, v29
	s_lshl_b32 s16, s20, 7
	v_and_b32_e32 v21, 0xe00, v40
	v_lshlrev_b32_e32 v19, 2, v19
	v_or3_b32 v21, v39, v28, v21
	global_load_dword v109, v19, s[38:39]
	global_load_dword v110, v19, s[38:39] offset:64
	global_load_dword v111, v19, s[38:39] offset:128
	global_load_dword v112, v19, s[38:39] offset:192
	v_lshlrev_b32_e32 v98, 1, v21
	s_mov_b64 s[0:1], 0x6000000
	v_lshl_add_u64 v[28:29], s[8:9], 0, v[98:99]
	v_lshl_add_u64 v[100:101], v[28:29], 0, s[0:1]
	v_ashrrev_i32_e32 v42, 2, v26
	v_lshlrev_b32_e32 v98, 5, v37
	v_lshlrev_b32_e32 v43, 4, v26
	v_and_b32_e32 v43, 48, v43
	v_and_b32_e32 v44, 0xc0, v26
	v_add3_u32 v43, 0, v44, v43
	v_mbcnt_lo_u32_b32 v44, -1, 0
	v_mbcnt_hi_u32_b32 v44, -1, v44
	s_ashr_i32 s8, s7, 1
	v_and_b32_e32 v46, 64, v44
	v_xor_b32_e32 v45, 1, v44
	v_add_u32_e32 v46, 64, v46
	s_lshl_b32 s9, s8, 5
	v_cmp_lt_i32_e32 vcc, v45, v46
	s_add_i32 s10, s9, s4
	s_add_i32 s4, s10, 0x800
	v_cndmask_b32_e32 v45, v44, v45, vcc
	v_lshlrev_b32_e32 v113, 2, v45
	v_xor_b32_e32 v45, 2, v44
	s_ashr_i32 s4, s4, 8
	v_cmp_lt_i32_e32 vcc, v45, v46
	ds_write_b128 v20, v[2:5]
	ds_write_b128 v22, v[6:9]
	s_waitcnt vmcnt(7)
	ds_write_b128 v24, v[10:13]
	s_waitcnt vmcnt(6)
; #define LAS __attribute__((address_space(3)))
; __device__ __forceinline__ void sgu_phase(LAS unsigned char* lds, const bf16_t* PROJ, const float* VST, const bf16_t* SW, const float* ln_g, const float* ln_b, const float* sgu_b,
;                                           bf16_t* Y, float* SS, int bx, int G) {
;     ...
;     const int dch = tid & 127; const float gch = ln_g[h * 128 + dch], bch = ln_b[h * 128 + dch];
;     const int dp = wid >> 1, th = wid & 1;
;     float bias[4];
; #pragma unroll
;     for (int jj = 0; jj < 4; ++jj) bias[jj] = sgu_b[h * 128 + 16 * (4 * th + jj) + fr];
;     u32x4 vst[4]; f32x4 sp[2];
;     ...
;     SGU_LOAD(cc);
;     for (; cc < 128; cc += step) {
;         const int T0 = cc * 128;
; #pragma unroll
;         for (int it = 0; it < 4; ++it) { const int p = tid + 512 * it, sb_ = p >> 6, row = 16 * (sb_ >> 2) + ((p >> 2) & 15), c16 = 4 * (sb_ & 3) + (p & 3); *(LAS u32x4*)(lds + SG_VS + row * SG_ROWB + c16 * 16) = vst[it]; }
;         { float s1 = (sp[0][0] + sp[0][2]) + (sp[1][0] + sp[1][2]), s2 = (sp[0][1] + sp[0][3]) + (sp[1][1] + sp[1][3]);
;           s1 += __shfl_xor(s1, 1); s1 += __shfl_xor(s1, 2); s2 += __shfl_xor(s2, 1); s2 += __shfl_xor(s2, 2);
;           const float mean = s1 * (1.0f / 1024.0f), var = fmaxf(s2 * (1.0f / 1024.0f) - mean * mean, 0.f);
;           if ((tid & 3) == 0) { meanp[tid >> 2] = mean; rstdp[tid >> 2] = 1.0f / sqrtf(var + EPS); } }
;         u32x4 uu[4], gg[4];
; #pragma unroll
;         for (int jj = 0; jj < 4; ++jj) { const int tk = T0 + 16 * (4 * th + jj) + fr, cl = h * 128 + 32 * dp + 8 * fq; uu[jj] = *(const u32x4*)PJ(PROJ, tk, COL_U + cl); gg[jj] = *(const u32x4*)PJ(PROJ, tk, COL_GB + cl); }
;         __syncthreads();
;         if (cc + step < 128) SGU_LOAD(cc + step);
	ds_write_b128 v18, v[14:17]
	v_add_u32_e32 v2, s16, v34
	v_ashrrev_i32_e32 v2, 4, v2
	v_add_u32_e32 v4, s16, v33
	v_ashrrev_i32_e32 v3, 31, v2
	v_ashrrev_i32_e32 v4, 4, v4
	v_lshlrev_b64 v[2:3], 13, v[2:3]
	v_ashrrev_i32_e32 v5, 31, v4
	v_lshl_add_u64 v[2:3], v[100:101], 0, v[2:3]
	v_lshlrev_b64 v[4:5], 13, v[4:5]
	v_lshl_add_u64 v[4:5], v[100:101], 0, v[4:5]
	global_load_dwordx4 v[14:17], v[2:3], off
	global_load_dwordx4 v[10:13], v[4:5], off
	v_add_u32_e32 v2, s16, v32
	v_ashrrev_i32_e32 v2, 4, v2
	v_ashrrev_i32_e32 v3, 31, v2
	v_lshlrev_b64 v[2:3], 13, v[2:3]
	v_lshl_add_u64 v[18:19], v[100:101], 0, v[2:3]
	v_add_u32_e32 v2, s16, v31
	v_ashrrev_i32_e32 v2, 4, v2
	v_ashrrev_i32_e32 v3, 31, v2
	v_lshlrev_b64 v[2:3], 13, v[2:3]
	v_lshl_add_u64 v[20:21], v[100:101], 0, v[2:3]
	global_load_dwordx4 v[6:9], v[18:19], off
	global_load_dwordx4 v[2:5], v[20:21], off
	v_add_u32_e32 v18, s16, v42
	v_ashrrev_i32_e32 v19, 31, v18
	v_lshlrev_b64 v[18:19], 7, v[18:19]
	v_lshl_add_u64 v[18:19], s[54:55], 0, v[18:19]
	v_lshl_add_u64 v[28:29], v[18:19], 0, v[98:99]
	global_load_dwordx4 v[18:21], v[28:29], off offset:16
	global_load_dwordx4 v[22:25], v[28:29], off
	s_ashr_i32 s5, s4, 31
	s_add_i32 s14, 0, 0x19c00
	v_cndmask_b32_e32 v45, v44, v45, vcc
	s_add_i32 s15, 0, 0x19800
	s_add_i32 s19, 0, 0x19a00
	s_lshl_b64 s[4:5], s[4:5], 23
	v_lshlrev_b32_e32 v114, 2, v45
	v_and_b32_e32 v45, -4, v26
	s_add_u32 s4, s36, s4
	v_add_u32_e32 v115, s15, v45
	v_add_u32_e32 v116, s19, v45
	s_addc_u32 s5, s37, s5
	s_lshl_b32 s11, s10, 4
	v_lshlrev_b32_e32 v45, 5, v26
	v_bfe_u32 v35, v26, 4, 2
	s_and_b32 s11, s11, 0xe00
	v_and_b32_e32 v45, 0x1e0, v45
	v_or_b32_e32 v45, s11, v45
	v_lshlrev_b32_e32 v117, 4, v35
	v_lshl_add_u64 v[102:103], s[54:55], 0, v[98:99]
	v_lshl_or_b32 v98, v45, 1, v117
	v_xor_b32_e32 v49, 16, v44
	v_lshl_add_u64 v[104:105], s[4:5], 0, v[98:99]
	s_add_i32 s4, s10, 0x1000
	v_cmp_lt_i32_e32 vcc, v49, v46
	s_ashr_i32 s4, s4, 8
	s_ashr_i32 s5, s4, 31
	v_cndmask_b32_e32 v49, v44, v49, vcc
	v_lshlrev_b32_e32 v119, 2, v49
	v_xor_b32_e32 v49, 32, v44
	s_lshl_b64 s[4:5], s[4:5], 23
	v_cmp_lt_i32_e32 vcc, v49, v46
	s_add_u32 s4, s36, s4
	v_ashrrev_i32_e32 v45, 7, v26
	v_cndmask_b32_e32 v44, v44, v49, vcc
	v_lshrrev_b32_e32 v29, 2, v26
	s_addc_u32 s5, s37, s5
	v_lshlrev_b32_e32 v120, 2, v44
	v_add_u32_e32 v44, 4, v45
	v_and_b32_e32 v38, -16, v31
	v_and_b32_e32 v39, -16, v32
	v_and_b32_e32 v40, -16, v33
	v_and_b32_e32 v41, -16, v34
	v_lshl_add_u64 v[106:107], s[4:5], 0, v[98:99]
	v_lshl_add_u32 v118, v36, 1, 0
	s_movk_i32 s4, 0x10e
	v_lshlrev_b32_e32 v47, 1, v26
	v_bfi_b32 v31, -16, v31, v29
	v_bfi_b32 v32, -16, v32, v29
	v_bfi_b32 v33, -16, v33, v29
	v_bfi_b32 v29, -16, v34, v29
	v_lshlrev_b32_e32 v34, 5, v45
	v_lshlrev_b32_e32 v49, 5, v44
	v_mad_u32_u24 v36, v36, s4, v118
	v_and_b32_e32 v47, 24, v47
	v_add_u32_e32 v48, s13, v117
	s_addk_i32 s10, 0x400
	s_lshl_b32 s4, s8, 10
	s_movk_i32 s13, 0x880
	v_add_u32_e32 v122, s15, v34
	v_add_u32_e32 v123, s19, v34
	v_or_b32_e32 v34, 16, v34
	v_add_u32_e32 v126, s15, v49
	v_add_u32_e32 v127, s19, v49
	v_or_b32_e32 v49, 16, v49
	v_cmp_eq_u32_e64 s[0:1], 0, v37
	v_or3_b32 v37, s9, v47, v37
	s_ashr_i32 s10, s10, 6
	s_and_b32 s55, s4, 0x400
	v_cmp_eq_u32_e64 s[8:9], 0, v35
	s_lshl_b32 s4, s7, 9
	v_mul_lo_u32 v121, v45, s13
	v_lshl_or_b32 v35, v45, 3, 1
	v_add_u32_e32 v124, s15, v34
	v_add_u32_e32 v125, s19, v34
	v_lshlrev_b32_e32 v34, 4, v45
	v_add_u32_e32 v128, s15, v49
	v_add_u32_e32 v129, s19, v49
	v_add_u32_e32 v49, 8, v45
	v_add_u32_e32 v45, 12, v45
	v_lshl_add_u32 v28, v26, 2, s14
	s_lshl_b32 s38, s17, 2
	s_ashr_i32 s11, s10, 31
	s_add_i32 s14, s14, s4
	v_lshlrev_b32_e32 v52, 5, v49
	v_lshlrev_b32_e32 v54, 5, v45
	v_lshl_or_b32 v50, v44, 3, 1
	v_add_u32_e32 v130, s15, v52
	v_add_u32_e32 v131, s19, v52
	v_lshl_or_b32 v53, v49, 3, 1
	v_or_b32_e32 v52, 16, v52
	v_add_u32_e32 v134, s15, v54
	v_add_u32_e32 v135, s19, v54
	v_lshl_or_b32 v55, v45, 3, 1
	v_or_b32_e32 v54, 16, v54
	s_bitcmp1_b32 s7, 0
	v_mul_lo_u32 v31, v31, s12
	v_mul_lo_u32 v32, v32, s12
	v_mul_lo_u32 v33, v33, s12
	v_mul_lo_u32 v29, v29, s12
	v_mul_lo_u32 v35, v35, s12
	v_mul_lo_u32 v50, v50, s12
	v_mul_lo_u32 v53, v53, s12
	v_add_u32_e32 v132, s15, v52
	v_mul_lo_u32 v55, v55, s12
	v_add_u32_e32 v136, s15, v54
	v_add_u32_e32 v137, s19, v54
	v_mul_lo_u32 v37, v37, s12
	v_or_b32_e32 v54, s18, v30
	s_cselect_b64 s[12:13], -1, 0
	s_or_b32 s15, s38, 1
	v_add_u32_e32 v133, s19, v52
	v_mul_u32_u24_e32 v56, 0x110, v54
	v_lshl_add_u32 v138, v54, 2, s14
	v_lshl_or_b32 v54, s15, 4, v30
	s_or_b32 s19, s38, 2
	s_or_b32 s38, s38, 3
	s_lshl_b32 s7, s17, 13
	v_mul_u32_u24_e32 v57, 0x110, v54
	s_lshl_b32 s15, s15, 11
	v_lshl_add_u32 v139, v54, 2, s14
	v_lshl_or_b32 v54, s19, 4, v30
	s_lshl_b32 s19, s19, 11
	s_lshl_b32 s59, s38, 11
	v_mul_u32_u24_e32 v58, 0x110, v54
	v_lshl_add_u32 v140, v54, 2, s14
	v_lshl_or_b32 v54, s38, 4, v30
	s_or_b32 s38, s7, s55
	s_or_b32 s39, s15, s55
	s_or_b32 s54, s19, s55
	s_or_b32 s55, s59, s55
	s_lshl_b32 s6, s6, 2
	v_lshl_add_u32 v141, v54, 2, s14
	s_add_u32 s14, s46, s6
	s_addc_u32 s15, s47, 0
	s_add_i32 s6, s20, s21
	s_lshl_b32 s6, s6, 7
	v_add_u32_e32 v47, 0, v117
	s_movk_i32 s4, 0x80
	v_lshlrev_b32_e32 v27, 9, v27
	v_add_u32_e32 v46, 0x2200, v121
	v_lshlrev_b32_e32 v44, 4, v44
	v_add_u32_e32 v51, 0x4400, v121
	v_lshlrev_b32_e32 v49, 4, v49
	v_add_u32_e32 v52, 0x6600, v121
	v_lshlrev_b32_e32 v45, 4, v45
	v_mul_u32_u24_e32 v59, 0x110, v54
	v_add_u32_e32 v142, s6, v42
	v_add_u32_e32 v143, s6, v41
	v_add_u32_e32 v144, s6, v40
	v_add_u32_e32 v145, s6, v39
	v_add_u32_e32 v146, s6, v38
	s_lshl_b32 s6, s20, 13
	s_lshl_b32 s7, s17, 12
	s_or_b32 s64, s16, s18
	s_mov_b32 s58, 0
	v_cmp_gt_i32_e64 s[4:5], s4, v26
	s_mul_i32 s59, s20, 48
	s_mul_i32 s60, s21, 48
	s_lshl_b32 s61, s21, 7
	v_add_u32_e32 v147, s16, v26
	v_lshlrev_b32_e32 v148, 6, v30
	s_or_b32 s62, s6, s7
	s_lshl_b32 s63, s21, 13
	v_or_b32_e32 v149, s64, v30
	v_add_u32_e32 v150, v43, v31
	v_add_u32_e32 v151, v43, v32
	v_add_u32_e32 v152, v43, v33
	v_add_u32_e32 v153, v43, v29
	s_mov_b32 s65, 0x3a800000
	s_mov_b32 s66, 0xf800000
	v_mov_b32_e32 v154, 0x260
	v_add_u32_e32 v155, v118, v35
	v_add_u32_e32 v156, v36, v34
	v_add_u32_e32 v157, v118, v46
	v_add_u32_e32 v158, v118, v50
	v_add_u32_e32 v159, v36, v44
	v_add_u32_e32 v160, v118, v51
	v_add_u32_e32 v161, v118, v53
	v_add_u32_e32 v162, v36, v49
	v_add_u32_e32 v163, v118, v52
	v_add_u32_e32 v164, v118, v55
	v_add_u32_e32 v165, v36, v45
	v_add_u32_e32 v166, v47, v37
	s_movk_i32 s67, 0x3c0
	v_add_u32_e32 v167, v28, v27
	v_add_u32_e32 v168, v48, v56
	v_add_u32_e32 v169, v48, v57
	v_add_u32_e32 v170, v48, v58
	v_add_u32_e32 v171, v48, v59
	s_branch .LBB0_633

; #define LAS __attribute__((address_space(3)))
; __device__ __forceinline__ void sgu_phase(LAS unsigned char* lds, const bf16_t* PROJ, const float* VST, const bf16_t* SW, const float* ln_g, const float* ln_b, const float* sgu_b,
;                                           bf16_t* Y, float* SS, int bx, int G) {
;     ...
;     SGU_LOAD(cc);
;     for (; cc < 128; cc += step) {
;         const int T0 = cc * 128;
; #pragma unroll
;         for (int it = 0; it < 4; ++it) { const int p = tid + 512 * it, sb_ = p >> 6, row = 16 * (sb_ >> 2) + ((p >> 2) & 15), c16 = 4 * (sb_ & 3) + (p & 3); *(LAS u32x4*)(lds + SG_VS + row * SG_ROWB + c16 * 16) = vst[it]; }
;         { float s1 = (sp[0][0] + sp[0][2]) + (sp[1][0] + sp[1][2]), s2 = (sp[0][1] + sp[0][3]) + (sp[1][1] + sp[1][3]);
;           s1 += __shfl_xor(s1, 1); s1 += __shfl_xor(s1, 2); s2 += __shfl_xor(s2, 1); s2 += __shfl_xor(s2, 2);
;           const float mean = s1 * (1.0f / 1024.0f), var = fmaxf(s2 * (1.0f / 1024.0f) - mean * mean, 0.f);
;           if ((tid & 3) == 0) { meanp[tid >> 2] = mean; rstdp[tid >> 2] = 1.0f / sqrtf(var + EPS); } }
;         u32x4 uu[4], gg[4];
; #pragma unroll
;         for (int jj = 0; jj < 4; ++jj) { const int tk = T0 + 16 * (4 * th + jj) + fr, cl = h * 128 + 32 * dp + 8 * fq; uu[jj] = *(const u32x4*)PJ(PROJ, tk, COL_U + cl); gg[jj] = *(const u32x4*)PJ(PROJ, tk, COL_GB + cl); }
;         __syncthreads();
;         if (cc + step < 128) SGU_LOAD(cc + step);
.LBB0_635:
	s_or_b64 exec, exec, s[16:17]
	s_add_i32 s6, s64, s58
	s_ashr_i32 s6, s6, 4
	s_ashr_i32 s7, s6, 31
	s_lshl_b64 s[16:17], s[6:7], 13
	s_waitcnt lgkmcnt(1)
	v_lshl_add_u64 v[26:27], v[104:105], 0, s[16:17]
	s_waitcnt lgkmcnt(0)
	v_lshl_add_u64 v[28:29], v[106:107], 0, s[16:17]
	s_or_b32 s16, s6, 1
	s_ashr_i32 s17, s16, 31
	s_lshl_b64 s[16:17], s[16:17], 13
	global_load_dwordx4 v[54:57], v[26:27], off
	global_load_dwordx4 v[50:53], v[28:29], off
	v_lshl_add_u64 v[26:27], v[104:105], 0, s[16:17]
	v_lshl_add_u64 v[28:29], v[106:107], 0, s[16:17]
	s_or_b32 s16, s6, 2
	s_ashr_i32 s17, s16, 31
	s_or_b32 s6, s6, 3
	s_lshl_b64 s[16:17], s[16:17], 13
	s_ashr_i32 s7, s6, 31
	global_load_dwordx4 v[46:49], v[26:27], off
	global_load_dwordx4 v[42:45], v[28:29], off
	v_lshl_add_u64 v[26:27], v[104:105], 0, s[16:17]
	v_lshl_add_u64 v[28:29], v[106:107], 0, s[16:17]
	s_lshl_b64 s[6:7], s[6:7], 13
	global_load_dwordx4 v[38:41], v[26:27], off
	global_load_dwordx4 v[34:37], v[28:29], off
	v_lshl_add_u64 v[26:27], v[104:105], 0, s[6:7]
	v_lshl_add_u64 v[28:29], v[106:107], 0, s[6:7]
	global_load_dwordx4 v[30:33], v[26:27], off
	s_nop 0
	global_load_dwordx4 v[26:29], v[28:29], off
	s_add_i32 s20, s20, s21
	s_cmp_gt_i32 s20, m0
	s_cselect_b64 s[16:17], -1, 0
	s_and_b64 vcc, exec, s[16:17]
	s_barrier
	s_cbranch_vccnz .LBB0_637
	v_add_u32_e32 v2, s58, v146
	v_add_u32_e32 v4, s58, v145
	v_add_u32_e32 v10, s58, v144
	v_add_u32_e32 v12, s58, v143
	v_ashrrev_i32_e32 v2, 4, v2
	v_ashrrev_i32_e32 v4, 4, v4
	v_ashrrev_i32_e32 v10, 4, v10
	v_ashrrev_i32_e32 v12, 4, v12
	v_add_u32_e32 v18, s58, v142
	v_ashrrev_i32_e32 v3, 31, v2
	v_ashrrev_i32_e32 v5, 31, v4
	v_ashrrev_i32_e32 v11, 31, v10
	v_ashrrev_i32_e32 v13, 31, v12
	v_ashrrev_i32_e32 v19, 31, v18
	v_lshlrev_b64 v[2:3], 13, v[2:3]
	v_lshlrev_b64 v[4:5], 13, v[4:5]
	v_lshlrev_b64 v[10:11], 13, v[10:11]
	v_lshlrev_b64 v[12:13], 13, v[12:13]
	v_lshlrev_b64 v[18:19], 7, v[18:19]
	v_lshl_add_u64 v[2:3], v[100:101], 0, v[2:3]
	v_lshl_add_u64 v[6:7], v[100:101], 0, v[4:5]
	v_lshl_add_u64 v[10:11], v[100:101], 0, v[10:11]
	v_lshl_add_u64 v[14:15], v[100:101], 0, v[12:13]
	v_lshl_add_u64 v[22:23], v[102:103], 0, v[18:19]
	global_load_dwordx4 v[2:5], v[2:3], off
	s_nop 0
	global_load_dwordx4 v[6:9], v[6:7], off
	s_nop 0
	global_load_dwordx4 v[10:13], v[10:11], off
	s_nop 0
	global_load_dwordx4 v[14:17], v[14:15], off
	s_nop 0
	global_load_dwordx4 v[18:21], v[22:23], off offset:16
	s_nop 0
	global_load_dwordx4 v[22:25], v[22:23], off

; #define LAS __attribute__((address_space(3)))
; __device__ __forceinline__ void attn_phase(LAS unsigned char* lds, const bf16_t* PROJ, const bf16_t* KM, const bf16_t* VT, bf16_t* Y, float* SS, int bx, int G, int tid) {
;     const int lane = tid & 63, wid = __builtin_amdgcn_readfirstlane(tid >> 6), fr = lane & 15, fq = lane >> 4;
;     int u = bx; if (u >= 512) return;
;     const int srow = tid >> 5, sc16 = tid & 31, sdst = srow * ATT_ROWB + ((sc16 ^ srow) << 4);
;     const int vs_ = sc16 & 3, vblk4_ = (sc16 >> 2) * 4;
;     const int rho0_ = 16 * ((srow >> 2) & 1) + 4 * (srow >> 3) + (srow & 3), vsw_ = rho0_ & 15;
;     const int vdst0 = rho0_ * ATT_ROWB + (((vblk4_ + ((2 * vs_) & 3)) ^ vsw_) << 4) + 8 * (vs_ >> 1);
;     const int frd = fr * ATT_ROWB + ((fq ^ fr) << 4);
;     int T0 = (u >> 2) * 128, h = u & 3, b = T0 / SEQ;
;     const bf16_t* ksrc = KM + ((size_t)(b * 4 + h) * 256 + srow) * 256 + sc16 * 8;
;     const bf16_t* vsrc = VT + ((size_t)(h * 4 + b) * 256 + srow) * 256 + sc16 * 8;
; __global__ void __launch_bounds__(NTHR, 2) mk_fwd(Args a) {
;     ...
;         const bool late_attn = ((bx >> 3) & 1) != 0;
;         if (!late_attn) attn_phase(lds, Proj, Kmat, VTm, Yb, SS, bx, G, tid);
;         pool_phase(lds, Proj, PoolWT, pool_scale, Yb, SS, bx, G);
;         sgu_phase(lds, Proj, VST, SguW, sgu_ln_g, sgu_ln_b, sgu_b, Yb, SS, bx, G);
;         if (late_attn) { int tid2 = threadIdx.x, bx2 = blockIdx.x; asm volatile("" : "+v"(tid2), "+s"(bx2));
;             attn_phase(lds, Proj, Kmat, VTm, Yb, SS, bx2, G, tid2); }
.LBB0_664:
	s_andn2_b64 vcc, exec, s[56:57]
	s_cbranch_vccnz .LBB0_679
	s_waitcnt vmcnt(0) lgkmcnt(0)
	v_mov_b32_e32 v1, s85
	ds_read_b32 v2, v1 offset:8
	ds_read_b32 v1, v1 offset:12
	s_waitcnt lgkmcnt(0)
	v_readfirstlane_b32 s0, v2
	v_readfirstlane_b32 s1, v1
	s_nop 3
	s_movk_i32 m0, 0x200
	s_cmp_eq_u32 s1, 0
	s_cbranch_scc0 .Lp2v_d
	s_and_b32 s4, s0, 7
	s_lshl_b32 s4, s4, 6
	s_lshr_b32 s5, s0, 3
	s_add_i32 s2, s4, s5
	s_add_i32 m0, s4, 64
.Lp2v_d:
	s_lshl_b32 s0, s74, 23
	s_add_u32 s6, s36, s0
	s_addc_u32 s7, s37, 0
	s_branch .Lattn_entry

; __device__ __forceinline__ unsigned xb_ld(unsigned* p)              { return __hip_atomic_load(p, __ATOMIC_RELAXED, __HIP_MEMORY_SCOPE_AGENT); }
; __device__ __forceinline__ unsigned xb_add(unsigned* p, unsigned v) { return __hip_atomic_fetch_add(p, v, __ATOMIC_RELAXED, __HIP_MEMORY_SCOPE_AGENT); }
; #define XB_SPIN(cond, bar) do { unsigned _sp = 0; while (cond) { __builtin_amdgcn_s_sleep(1); \
;     if ((++_sp & 255u) == 0u) { if (xb_ld(&(bar)[XB_TMO])) break; if (_sp > XB_SPIN_CAP) { atomicAdd(&(bar)[XB_TMO], 1u); break; } } } } while (0)
; __device__ __forceinline__ void xcd_barrier(const XcdBarrier& b) {
;     asm volatile("s_waitcnt vmcnt(0)" ::: "memory");
;     __syncthreads();
;     if (threadIdx.x == 0) {
;         unsigned* bar = b.bar;
;         __builtin_amdgcn_s_waitcnt(0);
;         unsigned nloc = b.st[0], nx = b.st[1];
;         if (nloc == 0u) { xcd_barrier_complete(bar, b.x, nloc, nx); b.st[0] = nloc; b.st[1] = nx; }
;         const unsigned old = xb_add(&bar[XB_XSUB(b.x)], 1u);
;         const unsigned gen = old / nloc;
;         if (old + 1u == (gen + 1u) * nloc) {
;             __builtin_amdgcn_fence(__ATOMIC_RELEASE, "agent");
;             asm volatile("s_waitcnt vmcnt(0)" ::: "memory");
;             const unsigned og = xb_add(&bar[XB_TOP], 1u);
;             const unsigned tg = og / nx;
;             if (og + 1u == (tg + 1u) * nx) xb_add(&bar[XB_TOPGEN], 1u);
;             else XB_SPIN(xb_ld(&bar[XB_TOPGEN]) == tg, bar);
;             __builtin_amdgcn_fence(__ATOMIC_ACQUIRE, "agent");
;             xb_add(&bar[XB_XGEN(b.x)], 1u);
;             asm volatile("s_waitcnt vmcnt(0)" ::: "memory");
;         } else {
;             XB_SPIN(xb_ld(&bar[XB_XGEN(b.x)]) == gen, bar);
;             __builtin_amdgcn_fence(__ATOMIC_ACQUIRE, "agent");
;             asm volatile("s_waitcnt vmcnt(0)" ::: "memory");
;         }
.LBB0_679:
	v_mov_b32_e32 v1, s85
	ds_read_b32 v2, v1 offset:8
	ds_read_b32 v1, v1 offset:12
	s_waitcnt lgkmcnt(0)
	v_readfirstlane_b32 s0, v2
	v_readfirstlane_b32 s1, v1
	s_nop 3
	s_mov_b32 s2, s0
	s_cmp_eq_u32 s1, 0
	s_cselect_b32 s3, 0x100, s3
	s_cmp_lt_i32 s27, 5
	s_cbranch_scc1 .LBB0_729
	s_waitcnt vmcnt(0) lgkmcnt(0)
	s_barrier
	v_cmp_eq_u32_e32 vcc, 0, v0
	s_and_saveexec_b64 s[0:1], vcc
	s_cbranch_execz .Lgb3_join
	v_mov_b32_e32 v1, s85
	ds_read_b32 v2, v1
	ds_read_b32 v3, v1 offset:4
	ds_read_b32 v4, v1 offset:12
	s_waitcnt lgkmcnt(0)
	v_readfirstlane_b32 s6, v2
	v_readfirstlane_b32 s7, v3
	v_readfirstlane_b32 s14, v4
	s_nop 3
	s_cmp_eq_u32 s14, 0
	s_cbranch_scc0 .Lgb3_global
	s_lshl_b32 s4, s84, 7
	s_addk_i32 s4, 0x3800
	v_mov_b32_e32 v4, s4
	v_mov_b32_e32 v5, 1
	global_atomic_add v4, v5, s[22:23]
	s_mov_b32 s11, 0

; __device__ __forceinline__ unsigned xb_ld(unsigned* p)              { return __hip_atomic_load(p, __ATOMIC_RELAXED, __HIP_MEMORY_SCOPE_AGENT); }
; __device__ __forceinline__ unsigned xb_add(unsigned* p, unsigned v) { return __hip_atomic_fetch_add(p, v, __ATOMIC_RELAXED, __HIP_MEMORY_SCOPE_AGENT); }
; #define XB_SPIN(cond, bar) do { unsigned _sp = 0; while (cond) { __builtin_amdgcn_s_sleep(1); \
;     if ((++_sp & 255u) == 0u) { if (xb_ld(&(bar)[XB_TMO])) break; if (_sp > XB_SPIN_CAP) { atomicAdd(&(bar)[XB_TMO], 1u); break; } } } } while (0)
; __device__ __forceinline__ void xcd_barrier(const XcdBarrier& b) {
;     ...
;         const unsigned old = xb_add(&bar[XB_XSUB(b.x)], 1u);
;         const unsigned gen = old / nloc;
;         if (old + 1u == (gen + 1u) * nloc) {
;             __builtin_amdgcn_fence(__ATOMIC_RELEASE, "agent");
;             asm volatile("s_waitcnt vmcnt(0)" ::: "memory");
;             const unsigned og = xb_add(&bar[XB_TOP], 1u);
;             const unsigned tg = og / nx;
;             if (og + 1u == (tg + 1u) * nx) xb_add(&bar[XB_TOPGEN], 1u);
;             else XB_SPIN(xb_ld(&bar[XB_TOPGEN]) == tg, bar);
;             __builtin_amdgcn_fence(__ATOMIC_ACQUIRE, "agent");
;             xb_add(&bar[XB_XGEN(b.x)], 1u);
;             asm volatile("s_waitcnt vmcnt(0)" ::: "memory");
.Lgb3_global:
	s_lshl_b32 s4, s84, 8
	s_add_u32 s4, s22, s4
	s_addc_u32 s5, s23, 0
	v_mov_b32_e32 v4, 0x1000
	v_mov_b32_e32 v5, 1
	global_atomic_add v5, v4, v5, s[4:5] offset:1024 sc0
	s_mul_i32 s14, s6, 4
	s_add_i32 s14, s14, -1
	s_mul_i32 s7, s7, 4
	v_mov_b32_e32 v3, 0x3400
	v_mov_b32_e32 v2, 1
	s_waitcnt vmcnt(0)
	v_readfirstlane_b32 s15, v5
	s_nop 3
	s_cmp_lg_u32 s15, s14
	s_cbranch_scc1 .Lgb3_poll
	buffer_wbl2 sc1
	s_waitcnt vmcnt(0)
	global_atomic_add v3, v2, s[22:23]

; __device__ __forceinline__ unsigned xb_ld(unsigned* p)              { return __hip_atomic_load(p, __ATOMIC_RELAXED, __HIP_MEMORY_SCOPE_AGENT); }
; #define XB_SPIN(cond, bar) do { unsigned _sp = 0; while (cond) { __builtin_amdgcn_s_sleep(1); \
;     if ((++_sp & 255u) == 0u) { if (xb_ld(&(bar)[XB_TMO])) break; if (_sp > XB_SPIN_CAP) { atomicAdd(&(bar)[XB_TMO], 1u); break; } } } } while (0)
; __device__ __forceinline__ void xcd_barrier(const XcdBarrier& b) {
;     ...
;             XB_SPIN(xb_ld(&bar[XB_XGEN(b.x)]) == gen, bar);
.Lgb4_lspin:
	global_load_dword v5, v4, s[22:23] sc1
	s_waitcnt vmcnt(0)
	v_readfirstlane_b32 s15, v5
	s_nop 3
	s_cmp_ge_u32 s15, 64
	s_cbranch_scc1 .Lgb4_acq
	s_sleep 1
	s_add_i32 s11, s11, 1
	s_cmp_lt_u32 s11, 0x8000
	s_cbranch_scc1 .Lgb4_lspin
	s_branch .Lgb4_acq
